# out-proj loop: every workgroup L2-prefetches its 1/32 share of the shared W_out K-tiles 4-7 tiles ahead (every 4th iteration)
# baseline (speedup 1.0000x reference)
; DI int opaque_tid() { int t = threadIdx.x; asm volatile("" : "+v"(t)); return t; }
; template <int NT2>
; DI void glu_prologue(const Params& p, char* lds, int l, int tile0, int tile1) {
;     const int tid = opaque_tid(), lane = tid & 63, wid = tid >> 6, l15 = lane & 15, quad = lane >> 4;
;     __syncthreads();
; #pragma unroll
;     for (int tt = 0; tt < NT2; ++tt) {
;         const int tile = tt ? tile1 : tile0;
;         char* Ys = lds + tt * 33792;
;         const bf16_t* ysg = WS_PTR(const bf16_t, OFF_YS) + (size_t)tile * 64 * 256;
; #pragma unroll
;         for (int i = 0; i < 4; ++i) {
;             const int idx = tid + NTHR * i, row = idx >> 5, c16 = idx & 31;
;             *(u32x4*)(Ys + row * 528 + c16 * 16) = *(const u32x4*)(ysg + (size_t)row * 256 + c16 * 8);
;         }
;     }
;     __syncthreads();
;     f32x4 acc[NT2][4][2];
; #pragma unroll
;     for (int tt = 0; tt < NT2; ++tt)
; #pragma unroll
;         for (int mt = 0; mt < 4; ++mt) { acc[tt][mt][0] = (f32x4){0.f, 0.f, 0.f, 0.f}; acc[tt][mt][1] = (f32x4){0.f, 0.f, 0.f, 0.f}; }
.LBB0_90:
	s_and_b64 vcc, exec, s[6:7]
	s_cbranch_vccz .LBB0_94
	s_ashr_i32 s35, s34, 31
	v_mov_b32_e32 v78, v212
	s_lshl_b64 s[8:9], s[34:35], 15
	v_readlane_b32 s40, v244, 46
	s_add_u32 s6, s40, s8
	v_lshlrev_b32_e32 v0, 4, v78
	v_ashrrev_i32_e32 v8, 5, v78
	v_readlane_b32 s47, v244, 47
	v_and_b32_e32 v0, 0x1f0, v0
	v_ashrrev_i32_e32 v9, 31, v8
	s_addc_u32 s7, s47, s9
	v_lshlrev_b64 v[10:11], 9, v[8:9]
	v_lshl_add_u64 v[12:13], s[6:7], 0, v[0:1]
	v_lshl_add_u64 v[2:3], v[12:13], 0, v[10:11]
	s_barrier
	global_load_dwordx4 v[172:175], v[2:3], off
	v_add_u32_e32 v6, 0, v0
	s_movk_i32 s46, 0x210
	v_mad_u64_u32 v[8:9], s[6:7], v8, s46, v[6:7]
	s_ashr_i32 s49, s48, 31
	v_and_b32_e32 v84, 15, v78
	v_ashrrev_i32_e32 v76, 6, v78
	v_bfe_u32 v79, v78, 4, 2
	v_mul_u32_u24_e32 v82, 0x210, v84
	v_add_u32_e32 v2, 0x200, v78
	v_ashrrev_i32_e32 v14, 5, v2
	v_ashrrev_i32_e32 v15, 31, v14
	v_lshlrev_b64 v[16:17], 9, v[14:15]
	v_lshl_add_u64 v[2:3], v[12:13], 0, v[16:17]
	global_load_dwordx4 v[176:179], v[2:3], off
	v_mad_u64_u32 v[14:15], s[6:7], v14, s46, v[6:7]
	v_add_u32_e32 v2, 0x400, v78
	v_ashrrev_i32_e32 v18, 5, v2
	v_ashrrev_i32_e32 v19, 31, v18
	v_lshlrev_b64 v[20:21], 9, v[18:19]
	v_lshl_add_u64 v[2:3], v[12:13], 0, v[20:21]
	global_load_dwordx4 v[180:183], v[2:3], off
	v_mad_u64_u32 v[18:19], s[6:7], v18, s46, v[6:7]
	v_add_u32_e32 v2, 0x600, v78
	v_ashrrev_i32_e32 v22, 5, v2
	v_ashrrev_i32_e32 v23, 31, v22
	v_lshlrev_b64 v[24:25], 9, v[22:23]
	v_lshl_add_u64 v[2:3], v[12:13], 0, v[24:25]
	global_load_dwordx4 v[184:187], v[2:3], off
	v_mad_u64_u32 v[6:7], s[6:7], v22, s46, v[6:7]
	s_lshl_b64 s[6:7], s[48:49], 15
	s_add_u32 s46, s40, s6
	s_addc_u32 s47, s47, s7
	v_lshl_add_u64 v[12:13], s[46:47], 0, v[0:1]
	v_lshlrev_b32_e32 v0, 8, v84
	s_mov_b64 s[46:47], 0
	v_lshl_add_u64 v[2:3], v[12:13], 0, v[10:11]
	global_load_dwordx4 v[188:191], v[2:3], off
	v_lshl_add_u64 v[2:3], v[12:13], 0, v[16:17]
	global_load_dwordx4 v[192:195], v[2:3], off
	v_lshl_add_u64 v[2:3], v[12:13], 0, v[20:21]
	global_load_dwordx4 v[196:199], v[2:3], off
	v_lshl_add_u64 v[2:3], v[12:13], 0, v[24:25]
	global_load_dwordx4 v[200:203], v[2:3], off
	v_lshl_or_b32 v2, v76, 13, v0
	v_ashrrev_i32_e32 v3, 31, v2
	v_lshlrev_b32_e32 v4, 4, v79
	v_lshlrev_b64 v[2:3], 1, v[2:3]
	v_or_b32_e32 v2, v2, v4
	v_lshl_add_u64 v[66:67], s[30:31], 0, v[2:3]
	v_lshrrev_b32_e32 v247, 5, v212
	v_add_u32_e32 v247, s33, v247
	v_and_b32_e32 v247, 31, v247
	v_and_b32_e32 v246, 31, v212
	v_lshlrev_b32_e32 v246, 7, v246
	v_lshl_or_b32 v247, v247, 12, v246
	s_lshl_b32 s94, s34, 17
	s_add_u32 s94, s54, s94
	s_addc_u32 s95, s55, 0
	global_load_dword v247, v247, s[94:95]
	v_add_co_u32_e32 v80, vcc, s87, v66
	s_nop 1
	v_addc_co_u32_e32 v81, vcc, 0, v67, vcc
	v_add_co_u32_e32 v102, vcc, s86, v66
	s_nop 1
	v_addc_co_u32_e32 v103, vcc, 0, v67, vcc
	global_load_dwordx4 v[104:107], v[80:81], off
	global_load_dwordx4 v[108:111], v[102:103], off
	global_load_dwordx4 v[112:115], v[80:81], off offset:64
	global_load_dwordx4 v[116:119], v[102:103], off offset:64
	global_load_dwordx4 v[120:123], v[80:81], off offset:128
	global_load_dwordx4 v[124:127], v[102:103], off offset:128
	global_load_dwordx4 v[128:131], v[80:81], off offset:192
	global_load_dwordx4 v[132:135], v[102:103], off offset:192
	global_load_dwordx4 v[140:143], v[80:81], off offset:256
	global_load_dwordx4 v[144:147], v[102:103], off offset:256
	global_load_dwordx4 v[148:151], v[80:81], off offset:320
	global_load_dwordx4 v[152:155], v[102:103], off offset:320
	global_load_dwordx4 v[156:159], v[80:81], off offset:384
	global_load_dwordx4 v[160:163], v[102:103], off offset:384
	global_load_dwordx4 v[164:167], v[80:81], off offset:448
	global_load_dwordx4 v[168:171], v[102:103], off offset:448
	s_waitcnt vmcnt(23)
	ds_write_b128 v8, v[172:175]
	s_waitcnt vmcnt(22)
	ds_write_b128 v14, v[176:179]
	s_waitcnt vmcnt(21)
	ds_write_b128 v18, v[180:183]
	s_waitcnt vmcnt(20)
	ds_write_b128 v6, v[184:187]
	s_waitcnt vmcnt(19)
	ds_write_b128 v8, v[188:191] offset:33792
	s_waitcnt vmcnt(18)
	ds_write_b128 v14, v[192:195] offset:33792
	s_waitcnt vmcnt(17)
	ds_write_b128 v18, v[196:199] offset:33792
	s_waitcnt vmcnt(16)
	ds_write_b128 v6, v[200:203] offset:33792
	v_mov_b32_e32 v2, 0
	v_add3_u32 v77, v82, v4, 0
	v_mov_b32_e32 v3, v2
	v_mov_b32_e32 v4, v2
	v_mov_b32_e32 v5, v2
	v_mov_b32_e32 v14, v2
	v_mov_b32_e32 v15, v2
	v_mov_b32_e32 v16, v2
	v_mov_b32_e32 v17, v2
	v_mov_b32_e32 v18, v2
	v_mov_b32_e32 v19, v2
	v_mov_b32_e32 v20, v2
	v_mov_b32_e32 v21, v2
	v_mov_b32_e32 v22, v2
	v_mov_b32_e32 v23, v2
	v_mov_b32_e32 v24, v2
	v_mov_b32_e32 v25, v2
	v_mov_b32_e32 v26, v2
	v_mov_b32_e32 v27, v2
	v_mov_b32_e32 v28, v2
	v_mov_b32_e32 v29, v2
	v_mov_b32_e32 v34, v2
	v_mov_b32_e32 v35, v2
	v_mov_b32_e32 v36, v2
	v_mov_b32_e32 v37, v2
	v_mov_b32_e32 v30, v2
	v_mov_b32_e32 v31, v2
	v_mov_b32_e32 v32, v2
	v_mov_b32_e32 v33, v2
	v_mov_b32_e32 v38, v2
	v_mov_b32_e32 v39, v2
	v_mov_b32_e32 v40, v2
	v_mov_b32_e32 v41, v2
	v_mov_b32_e32 v42, v2
	v_mov_b32_e32 v43, v2
	v_mov_b32_e32 v44, v2
	v_mov_b32_e32 v45, v2
	v_mov_b32_e32 v46, v2
	v_mov_b32_e32 v47, v2
	v_mov_b32_e32 v48, v2
	v_mov_b32_e32 v49, v2
	v_mov_b32_e32 v50, v2
	v_mov_b32_e32 v51, v2
	v_mov_b32_e32 v52, v2
	v_mov_b32_e32 v53, v2
	v_mov_b32_e32 v68, v2
	v_mov_b32_e32 v69, v2
	v_mov_b32_e32 v70, v2
	v_mov_b32_e32 v71, v2
	v_mov_b32_e32 v58, v2
	v_mov_b32_e32 v59, v2
	v_mov_b32_e32 v60, v2
	v_mov_b32_e32 v61, v2
	v_mov_b32_e32 v54, v2
	v_mov_b32_e32 v55, v2
	v_mov_b32_e32 v56, v2
	v_mov_b32_e32 v57, v2
	v_mov_b32_e32 v10, v2
	v_mov_b32_e32 v11, v2
	v_mov_b32_e32 v12, v2
	v_mov_b32_e32 v13, v2
	v_mov_b32_e32 v6, v2
	v_mov_b32_e32 v7, v2
	v_mov_b32_e32 v8, v2
	v_mov_b32_e32 v9, v2
	s_waitcnt lgkmcnt(0)
	s_barrier
; DI f32x4 mfma16(bf16x8 a, bf16x8 b, f32x4 c) { return __builtin_amdgcn_mfma_f32_16x16x32_bf16(a, b, c, 0, 0, 0); }
; template <int NT2>
; DI void glu_prologue(const Params& p, char* lds, int l, int tile0, int tile1) {
;     ...
; #pragma unroll 2
;     for (int ks = 0; ks < 8; ++ks) {
;         bf16x8 bb[2];
; #pragma unroll
;         for (int nt = 0; nt < 2; ++nt) bb[nt] = *(const bf16x8*)(Wg + (wid * 32 + nt * 16 + l15) * 256 + 32 * ks + 8 * quad);
; #pragma unroll
;         for (int tt = 0; tt < NT2; ++tt) {
;             const char* Ys = lds + tt * 33792;
;             bf16x8 a[4];
; #pragma unroll
;             for (int mt = 0; mt < 4; ++mt) a[mt] = *(const bf16x8*)(Ys + (mt * 16 + l15) * 528 + (32 * ks + 8 * quad) * 2);
; #pragma unroll
;             for (int mt = 0; mt < 4; ++mt)
; #pragma unroll
;                 for (int nt = 0; nt < 2; ++nt) acc[tt][mt][nt] = mfma16(bb[nt], a[mt], acc[tt][mt][nt]);
;         }
	s_waitcnt vmcnt(14)
	ds_read_b128 v[86:89], v77
	ds_read_b128 v[90:93], v77 offset:8448
	ds_read_b128 v[94:97], v77 offset:16896
	ds_read_b128 v[98:101], v77 offset:25344
	s_waitcnt lgkmcnt(3)
	v_mfma_f32_16x16x32_bf16 v[54:57], v[104:107], v[86:89], v[54:57]
	v_mfma_f32_16x16x32_bf16 v[58:61], v[108:111], v[86:89], v[58:61]
	s_waitcnt lgkmcnt(2)
	v_mfma_f32_16x16x32_bf16 v[68:71], v[104:107], v[90:93], v[68:71]
	v_mfma_f32_16x16x32_bf16 v[50:53], v[108:111], v[90:93], v[50:53]
	s_waitcnt lgkmcnt(1)
	v_mfma_f32_16x16x32_bf16 v[46:49], v[104:107], v[94:97], v[46:49]
	v_mfma_f32_16x16x32_bf16 v[42:45], v[108:111], v[94:97], v[42:45]
	s_waitcnt lgkmcnt(0)
	v_mfma_f32_16x16x32_bf16 v[38:41], v[104:107], v[98:101], v[38:41]
	v_mfma_f32_16x16x32_bf16 v[30:33], v[108:111], v[98:101], v[30:33]
	ds_read_b128 v[86:89], v77 offset:33792
	ds_read_b128 v[90:93], v77 offset:42240
	ds_read_b128 v[94:97], v77 offset:50688
	ds_read_b128 v[98:101], v77 offset:59136
	s_waitcnt lgkmcnt(3)
	v_mfma_f32_16x16x32_bf16 v[34:37], v[104:107], v[86:89], v[34:37]
	v_mfma_f32_16x16x32_bf16 v[26:29], v[108:111], v[86:89], v[26:29]
	s_waitcnt lgkmcnt(2)
	v_mfma_f32_16x16x32_bf16 v[22:25], v[104:107], v[90:93], v[22:25]
	v_mfma_f32_16x16x32_bf16 v[18:21], v[108:111], v[90:93], v[18:21]
	s_waitcnt lgkmcnt(1)
	v_mfma_f32_16x16x32_bf16 v[14:17], v[104:107], v[94:97], v[14:17]
	v_mfma_f32_16x16x32_bf16 v[2:5], v[108:111], v[94:97], v[2:5]
	s_waitcnt lgkmcnt(0)
	v_mfma_f32_16x16x32_bf16 v[10:13], v[104:107], v[98:101], v[10:13]
	v_mfma_f32_16x16x32_bf16 v[6:9], v[108:111], v[98:101], v[6:9]
	s_waitcnt vmcnt(12)
	ds_read_b128 v[86:89], v77 offset:64
	ds_read_b128 v[90:93], v77 offset:8512
	ds_read_b128 v[94:97], v77 offset:16960
	ds_read_b128 v[98:101], v77 offset:25408
	s_waitcnt lgkmcnt(3)
	v_mfma_f32_16x16x32_bf16 v[54:57], v[112:115], v[86:89], v[54:57]
	v_mfma_f32_16x16x32_bf16 v[58:61], v[116:119], v[86:89], v[58:61]
	s_waitcnt lgkmcnt(2)
	v_mfma_f32_16x16x32_bf16 v[68:71], v[112:115], v[90:93], v[68:71]
	v_mfma_f32_16x16x32_bf16 v[50:53], v[116:119], v[90:93], v[50:53]
	s_waitcnt lgkmcnt(1)
	v_mfma_f32_16x16x32_bf16 v[46:49], v[112:115], v[94:97], v[46:49]
	v_mfma_f32_16x16x32_bf16 v[42:45], v[116:119], v[94:97], v[42:45]
	s_waitcnt lgkmcnt(0)
	v_mfma_f32_16x16x32_bf16 v[38:41], v[112:115], v[98:101], v[38:41]
	v_mfma_f32_16x16x32_bf16 v[30:33], v[116:119], v[98:101], v[30:33]
	ds_read_b128 v[86:89], v77 offset:33856
	ds_read_b128 v[90:93], v77 offset:42304
	ds_read_b128 v[94:97], v77 offset:50752
	ds_read_b128 v[98:101], v77 offset:59200
	s_waitcnt lgkmcnt(3)
	v_mfma_f32_16x16x32_bf16 v[34:37], v[112:115], v[86:89], v[34:37]
	v_mfma_f32_16x16x32_bf16 v[26:29], v[116:119], v[86:89], v[26:29]
	s_waitcnt lgkmcnt(2)
	v_mfma_f32_16x16x32_bf16 v[22:25], v[112:115], v[90:93], v[22:25]
	v_mfma_f32_16x16x32_bf16 v[18:21], v[116:119], v[90:93], v[18:21]
	s_waitcnt lgkmcnt(1)
	v_mfma_f32_16x16x32_bf16 v[14:17], v[112:115], v[94:97], v[14:17]
	v_mfma_f32_16x16x32_bf16 v[2:5], v[116:119], v[94:97], v[2:5]
	s_waitcnt lgkmcnt(0)
	v_mfma_f32_16x16x32_bf16 v[10:13], v[112:115], v[98:101], v[10:13]
	v_mfma_f32_16x16x32_bf16 v[6:9], v[116:119], v[98:101], v[6:9]
	s_waitcnt vmcnt(10)
	ds_read_b128 v[86:89], v77 offset:128
	ds_read_b128 v[90:93], v77 offset:8576
	ds_read_b128 v[94:97], v77 offset:17024
	ds_read_b128 v[98:101], v77 offset:25472
	s_waitcnt lgkmcnt(3)
	v_mfma_f32_16x16x32_bf16 v[54:57], v[120:123], v[86:89], v[54:57]
	v_mfma_f32_16x16x32_bf16 v[58:61], v[124:127], v[86:89], v[58:61]
	s_waitcnt lgkmcnt(2)
	v_mfma_f32_16x16x32_bf16 v[68:71], v[120:123], v[90:93], v[68:71]
	v_mfma_f32_16x16x32_bf16 v[50:53], v[124:127], v[90:93], v[50:53]
	s_waitcnt lgkmcnt(1)
	v_mfma_f32_16x16x32_bf16 v[46:49], v[120:123], v[94:97], v[46:49]
	v_mfma_f32_16x16x32_bf16 v[42:45], v[124:127], v[94:97], v[42:45]
	s_waitcnt lgkmcnt(0)
	v_mfma_f32_16x16x32_bf16 v[38:41], v[120:123], v[98:101], v[38:41]
	v_mfma_f32_16x16x32_bf16 v[30:33], v[124:127], v[98:101], v[30:33]
	ds_read_b128 v[86:89], v77 offset:33920
	ds_read_b128 v[90:93], v77 offset:42368
	ds_read_b128 v[94:97], v77 offset:50816
	ds_read_b128 v[98:101], v77 offset:59264
	s_waitcnt lgkmcnt(3)
	v_mfma_f32_16x16x32_bf16 v[34:37], v[120:123], v[86:89], v[34:37]
	v_mfma_f32_16x16x32_bf16 v[26:29], v[124:127], v[86:89], v[26:29]
	s_waitcnt lgkmcnt(2)
	v_mfma_f32_16x16x32_bf16 v[22:25], v[120:123], v[90:93], v[22:25]
	v_mfma_f32_16x16x32_bf16 v[18:21], v[124:127], v[90:93], v[18:21]
	s_waitcnt lgkmcnt(1)
	v_mfma_f32_16x16x32_bf16 v[14:17], v[120:123], v[94:97], v[14:17]
	v_mfma_f32_16x16x32_bf16 v[2:5], v[124:127], v[94:97], v[2:5]
	s_waitcnt lgkmcnt(0)
	v_mfma_f32_16x16x32_bf16 v[10:13], v[120:123], v[98:101], v[10:13]
	v_mfma_f32_16x16x32_bf16 v[6:9], v[124:127], v[98:101], v[6:9]
	s_waitcnt vmcnt(8)
	ds_read_b128 v[86:89], v77 offset:192
	ds_read_b128 v[90:93], v77 offset:8640
	ds_read_b128 v[94:97], v77 offset:17088
	ds_read_b128 v[98:101], v77 offset:25536
	s_waitcnt lgkmcnt(3)
	v_mfma_f32_16x16x32_bf16 v[54:57], v[128:131], v[86:89], v[54:57]
	v_mfma_f32_16x16x32_bf16 v[58:61], v[132:135], v[86:89], v[58:61]
	s_waitcnt lgkmcnt(2)
	v_mfma_f32_16x16x32_bf16 v[68:71], v[128:131], v[90:93], v[68:71]
	v_mfma_f32_16x16x32_bf16 v[50:53], v[132:135], v[90:93], v[50:53]
	s_waitcnt lgkmcnt(1)
	v_mfma_f32_16x16x32_bf16 v[46:49], v[128:131], v[94:97], v[46:49]
	v_mfma_f32_16x16x32_bf16 v[42:45], v[132:135], v[94:97], v[42:45]
	s_waitcnt lgkmcnt(0)
	v_mfma_f32_16x16x32_bf16 v[38:41], v[128:131], v[98:101], v[38:41]
	v_mfma_f32_16x16x32_bf16 v[30:33], v[132:135], v[98:101], v[30:33]
	ds_read_b128 v[86:89], v77 offset:33984
	ds_read_b128 v[90:93], v77 offset:42432
	ds_read_b128 v[94:97], v77 offset:50880
	ds_read_b128 v[98:101], v77 offset:59328
	s_waitcnt lgkmcnt(3)
; DI f32x4 mfma16(bf16x8 a, bf16x8 b, f32x4 c) { return __builtin_amdgcn_mfma_f32_16x16x32_bf16(a, b, c, 0, 0, 0); }
; template <int NT2>
; DI void glu_prologue(const Params& p, char* lds, int l, int tile0, int tile1) {
;     ...
; #pragma unroll 2
;     for (int ks = 0; ks < 8; ++ks) {
;         bf16x8 bb[2];
; #pragma unroll
;         for (int nt = 0; nt < 2; ++nt) bb[nt] = *(const bf16x8*)(Wg + (wid * 32 + nt * 16 + l15) * 256 + 32 * ks + 8 * quad);
; #pragma unroll
;         for (int tt = 0; tt < NT2; ++tt) {
;             const char* Ys = lds + tt * 33792;
;             bf16x8 a[4];
; #pragma unroll
;             for (int mt = 0; mt < 4; ++mt) a[mt] = *(const bf16x8*)(Ys + (mt * 16 + l15) * 528 + (32 * ks + 8 * quad) * 2);
; #pragma unroll
;             for (int mt = 0; mt < 4; ++mt)
; #pragma unroll
;                 for (int nt = 0; nt < 2; ++nt) acc[tt][mt][nt] = mfma16(bb[nt], a[mt], acc[tt][mt][nt]);
;         }
	v_mfma_f32_16x16x32_bf16 v[34:37], v[128:131], v[86:89], v[34:37]
	v_mfma_f32_16x16x32_bf16 v[26:29], v[132:135], v[86:89], v[26:29]
	s_waitcnt lgkmcnt(2)
	v_mfma_f32_16x16x32_bf16 v[22:25], v[128:131], v[90:93], v[22:25]
	v_mfma_f32_16x16x32_bf16 v[18:21], v[132:135], v[90:93], v[18:21]
	s_waitcnt lgkmcnt(1)
	v_mfma_f32_16x16x32_bf16 v[14:17], v[128:131], v[94:97], v[14:17]
	v_mfma_f32_16x16x32_bf16 v[2:5], v[132:135], v[94:97], v[2:5]
	s_waitcnt lgkmcnt(0)
	v_mfma_f32_16x16x32_bf16 v[10:13], v[128:131], v[98:101], v[10:13]
	v_mfma_f32_16x16x32_bf16 v[6:9], v[132:135], v[98:101], v[6:9]
	s_waitcnt vmcnt(6)
	ds_read_b128 v[86:89], v77 offset:256
	ds_read_b128 v[90:93], v77 offset:8704
	ds_read_b128 v[94:97], v77 offset:17152
	ds_read_b128 v[98:101], v77 offset:25600
	s_waitcnt lgkmcnt(3)
	v_mfma_f32_16x16x32_bf16 v[54:57], v[140:143], v[86:89], v[54:57]
	v_mfma_f32_16x16x32_bf16 v[58:61], v[144:147], v[86:89], v[58:61]
	s_waitcnt lgkmcnt(2)
	v_mfma_f32_16x16x32_bf16 v[68:71], v[140:143], v[90:93], v[68:71]
	v_mfma_f32_16x16x32_bf16 v[50:53], v[144:147], v[90:93], v[50:53]
	s_waitcnt lgkmcnt(1)
	v_mfma_f32_16x16x32_bf16 v[46:49], v[140:143], v[94:97], v[46:49]
	v_mfma_f32_16x16x32_bf16 v[42:45], v[144:147], v[94:97], v[42:45]
	s_waitcnt lgkmcnt(0)
	v_mfma_f32_16x16x32_bf16 v[38:41], v[140:143], v[98:101], v[38:41]
	v_mfma_f32_16x16x32_bf16 v[30:33], v[144:147], v[98:101], v[30:33]
	ds_read_b128 v[86:89], v77 offset:34048
	ds_read_b128 v[90:93], v77 offset:42496
	ds_read_b128 v[94:97], v77 offset:50944
	ds_read_b128 v[98:101], v77 offset:59392
	s_waitcnt lgkmcnt(3)
	v_mfma_f32_16x16x32_bf16 v[34:37], v[140:143], v[86:89], v[34:37]
	v_mfma_f32_16x16x32_bf16 v[26:29], v[144:147], v[86:89], v[26:29]
	s_waitcnt lgkmcnt(2)
	v_mfma_f32_16x16x32_bf16 v[22:25], v[140:143], v[90:93], v[22:25]
	v_mfma_f32_16x16x32_bf16 v[18:21], v[144:147], v[90:93], v[18:21]
	s_waitcnt lgkmcnt(1)
	v_mfma_f32_16x16x32_bf16 v[14:17], v[140:143], v[94:97], v[14:17]
	v_mfma_f32_16x16x32_bf16 v[2:5], v[144:147], v[94:97], v[2:5]
	s_waitcnt lgkmcnt(0)
	v_mfma_f32_16x16x32_bf16 v[10:13], v[140:143], v[98:101], v[10:13]
	v_mfma_f32_16x16x32_bf16 v[6:9], v[144:147], v[98:101], v[6:9]
	s_waitcnt vmcnt(4)
	ds_read_b128 v[86:89], v77 offset:320
	ds_read_b128 v[90:93], v77 offset:8768
	ds_read_b128 v[94:97], v77 offset:17216
	ds_read_b128 v[98:101], v77 offset:25664
	s_waitcnt lgkmcnt(3)
	v_mfma_f32_16x16x32_bf16 v[54:57], v[148:151], v[86:89], v[54:57]
	v_mfma_f32_16x16x32_bf16 v[58:61], v[152:155], v[86:89], v[58:61]
	s_waitcnt lgkmcnt(2)
	v_mfma_f32_16x16x32_bf16 v[68:71], v[148:151], v[90:93], v[68:71]
	v_mfma_f32_16x16x32_bf16 v[50:53], v[152:155], v[90:93], v[50:53]
	s_waitcnt lgkmcnt(1)
	v_mfma_f32_16x16x32_bf16 v[46:49], v[148:151], v[94:97], v[46:49]
	v_mfma_f32_16x16x32_bf16 v[42:45], v[152:155], v[94:97], v[42:45]
	s_waitcnt lgkmcnt(0)
	v_mfma_f32_16x16x32_bf16 v[38:41], v[148:151], v[98:101], v[38:41]
	v_mfma_f32_16x16x32_bf16 v[30:33], v[152:155], v[98:101], v[30:33]
	ds_read_b128 v[86:89], v77 offset:34112
	ds_read_b128 v[90:93], v77 offset:42560
	ds_read_b128 v[94:97], v77 offset:51008
	ds_read_b128 v[98:101], v77 offset:59456
	s_waitcnt lgkmcnt(3)
	v_mfma_f32_16x16x32_bf16 v[34:37], v[148:151], v[86:89], v[34:37]
	v_mfma_f32_16x16x32_bf16 v[26:29], v[152:155], v[86:89], v[26:29]
	s_waitcnt lgkmcnt(2)
	v_mfma_f32_16x16x32_bf16 v[22:25], v[148:151], v[90:93], v[22:25]
	v_mfma_f32_16x16x32_bf16 v[18:21], v[152:155], v[90:93], v[18:21]
	s_waitcnt lgkmcnt(1)
	v_mfma_f32_16x16x32_bf16 v[14:17], v[148:151], v[94:97], v[14:17]
	v_mfma_f32_16x16x32_bf16 v[2:5], v[152:155], v[94:97], v[2:5]
	s_waitcnt lgkmcnt(0)
	v_mfma_f32_16x16x32_bf16 v[10:13], v[148:151], v[98:101], v[10:13]
	v_mfma_f32_16x16x32_bf16 v[6:9], v[152:155], v[98:101], v[6:9]
	s_waitcnt vmcnt(2)
	ds_read_b128 v[86:89], v77 offset:384
	ds_read_b128 v[90:93], v77 offset:8832
	ds_read_b128 v[94:97], v77 offset:17280
	ds_read_b128 v[98:101], v77 offset:25728
	s_waitcnt lgkmcnt(3)
	v_mfma_f32_16x16x32_bf16 v[54:57], v[156:159], v[86:89], v[54:57]
	v_mfma_f32_16x16x32_bf16 v[58:61], v[160:163], v[86:89], v[58:61]
	s_waitcnt lgkmcnt(2)
	v_mfma_f32_16x16x32_bf16 v[68:71], v[156:159], v[90:93], v[68:71]
	v_mfma_f32_16x16x32_bf16 v[50:53], v[160:163], v[90:93], v[50:53]
	s_waitcnt lgkmcnt(1)
	v_mfma_f32_16x16x32_bf16 v[46:49], v[156:159], v[94:97], v[46:49]
	v_mfma_f32_16x16x32_bf16 v[42:45], v[160:163], v[94:97], v[42:45]
	s_waitcnt lgkmcnt(0)
	v_mfma_f32_16x16x32_bf16 v[38:41], v[156:159], v[98:101], v[38:41]
	v_mfma_f32_16x16x32_bf16 v[30:33], v[160:163], v[98:101], v[30:33]
	ds_read_b128 v[86:89], v77 offset:34176
	ds_read_b128 v[90:93], v77 offset:42624
	ds_read_b128 v[94:97], v77 offset:51072
	ds_read_b128 v[98:101], v77 offset:59520
	s_waitcnt lgkmcnt(3)
	v_mfma_f32_16x16x32_bf16 v[34:37], v[156:159], v[86:89], v[34:37]
	v_mfma_f32_16x16x32_bf16 v[26:29], v[160:163], v[86:89], v[26:29]
	s_waitcnt lgkmcnt(2)
	v_mfma_f32_16x16x32_bf16 v[22:25], v[156:159], v[90:93], v[22:25]
	v_mfma_f32_16x16x32_bf16 v[18:21], v[160:163], v[90:93], v[18:21]
	s_waitcnt lgkmcnt(1)
	v_mfma_f32_16x16x32_bf16 v[14:17], v[156:159], v[94:97], v[14:17]
	v_mfma_f32_16x16x32_bf16 v[2:5], v[160:163], v[94:97], v[2:5]
	s_waitcnt lgkmcnt(0)
	v_mfma_f32_16x16x32_bf16 v[10:13], v[156:159], v[98:101], v[10:13]
	v_mfma_f32_16x16x32_bf16 v[6:9], v[160:163], v[98:101], v[6:9]
	s_waitcnt vmcnt(0)
	ds_read_b128 v[86:89], v77 offset:448
	ds_read_b128 v[90:93], v77 offset:8896
	ds_read_b128 v[94:97], v77 offset:17344
	ds_read_b128 v[98:101], v77 offset:25792
	s_waitcnt lgkmcnt(3)
; DI unsigned pk2(float lo, float hi) { const f32x2 v = {lo, hi}; const bf16x2_t b = __builtin_convertvector(v, bf16x2_t); return __builtin_bit_cast(unsigned, b); }
; DI float bf2f(unsigned b) { return __uint_as_float(b << 16); }
; template <int NT2>
; DI void glu_prologue(const Params& p, char* lds, int l, int tile0, int tile1) {
;     ...
;     for (int ks = 0; ks < 8; ++ks) {
;         bf16x8 bb[2];
; #pragma unroll
;         for (int nt = 0; nt < 2; ++nt) bb[nt] = *(const bf16x8*)(Wg + (wid * 32 + nt * 16 + l15) * 256 + 32 * ks + 8 * quad);
; #pragma unroll
;         for (int tt = 0; tt < NT2; ++tt) {
;             const char* Ys = lds + tt * 33792;
;             bf16x8 a[4];
; #pragma unroll
;             for (int mt = 0; mt < 4; ++mt) a[mt] = *(const bf16x8*)(Ys + (mt * 16 + l15) * 528 + (32 * ks + 8 * quad) * 2);
; #pragma unroll
;             for (int mt = 0; mt < 4; ++mt)
; #pragma unroll
;                 for (int nt = 0; nt < 2; ++nt) acc[tt][mt][nt] = mfma16(bb[nt], a[mt], acc[tt][mt][nt]);
;         }
;     ...
;     bf16_t* yo = WS_PTR(bf16_t, OFF_Y);
; #pragma unroll
;     for (int tt = 0; tt < NT2; ++tt) {
;         const int tile = tt ? tile1 : tile0;
;         const char* Ys = lds + tt * 33792;
;         const bf16_t* sg = WS_PTR(const bf16_t, OFF_SG) + (size_t)tile * 64 * 256;
; #pragma unroll
;         for (int mt = 0; mt < 4; ++mt) {
;             const int tok = mt * 16 + l15;
; #pragma unroll
;             for (int nt = 0; nt < 2; ++nt) {
;                 const int n0 = wid * 32 + nt * 16 + quad * 4;
;                 const f32x4 gb = *(const f32x4*)(p.glu_b + l * 256 + n0);
;                 const u32x2 yv = *(const u32x2*)(Ys + tok * 528 + n0 * 2);
;                 const u32x2 sv = *(const u32x2*)(sg + (size_t)tok * 256 + n0);
;                 float o[4];
;                 o[0] = sigmoid_f(acc[tt][mt][nt][0] + gb[0]) * bf2f(yv[0] & 0xffffu) * bf2f(sv[0] & 0xffffu);
;                 o[1] = sigmoid_f(acc[tt][mt][nt][1] + gb[1]) * bf2f(yv[0] >> 16) * bf2f(sv[0] >> 16);
;                 o[2] = sigmoid_f(acc[tt][mt][nt][2] + gb[2]) * bf2f(yv[1] & 0xffffu) * bf2f(sv[1] & 0xffffu);
;                 o[3] = sigmoid_f(acc[tt][mt][nt][3] + gb[3]) * bf2f(yv[1] >> 16) * bf2f(sv[1] >> 16);
;                 *(u32x2*)(yo + y_off(tile * 64 + tok, 512 + n0)) = (u32x2){pk2(o[0], o[1]), pk2(o[2], o[3])};
;             }
	v_mfma_f32_16x16x32_bf16 v[54:57], v[164:167], v[86:89], v[54:57]
	v_mfma_f32_16x16x32_bf16 v[58:61], v[168:171], v[86:89], v[58:61]
	s_waitcnt lgkmcnt(2)
	v_mfma_f32_16x16x32_bf16 v[68:71], v[164:167], v[90:93], v[68:71]
	v_mfma_f32_16x16x32_bf16 v[50:53], v[168:171], v[90:93], v[50:53]
	s_waitcnt lgkmcnt(1)
	v_mfma_f32_16x16x32_bf16 v[46:49], v[164:167], v[94:97], v[46:49]
	v_mfma_f32_16x16x32_bf16 v[42:45], v[168:171], v[94:97], v[42:45]
	s_waitcnt lgkmcnt(0)
	v_mfma_f32_16x16x32_bf16 v[38:41], v[164:167], v[98:101], v[38:41]
	v_mfma_f32_16x16x32_bf16 v[30:33], v[168:171], v[98:101], v[30:33]
	ds_read_b128 v[86:89], v77 offset:34240
	ds_read_b128 v[90:93], v77 offset:42688
	ds_read_b128 v[94:97], v77 offset:51136
	ds_read_b128 v[98:101], v77 offset:59584
	s_waitcnt lgkmcnt(3)
	v_mfma_f32_16x16x32_bf16 v[34:37], v[164:167], v[86:89], v[34:37]
	v_mfma_f32_16x16x32_bf16 v[26:29], v[168:171], v[86:89], v[26:29]
	s_waitcnt lgkmcnt(2)
	v_mfma_f32_16x16x32_bf16 v[22:25], v[164:167], v[90:93], v[22:25]
	v_mfma_f32_16x16x32_bf16 v[18:21], v[168:171], v[90:93], v[18:21]
	s_waitcnt lgkmcnt(1)
	v_mfma_f32_16x16x32_bf16 v[14:17], v[164:167], v[94:97], v[14:17]
	v_mfma_f32_16x16x32_bf16 v[2:5], v[168:171], v[94:97], v[2:5]
	s_waitcnt lgkmcnt(0)
	v_mfma_f32_16x16x32_bf16 v[10:13], v[164:167], v[98:101], v[10:13]
	v_mfma_f32_16x16x32_bf16 v[6:9], v[168:171], v[98:101], v[6:9]
	v_lshlrev_b32_e32 v66, 5, v76
	v_lshlrev_b32_e32 v62, 2, v79
	v_or_b32_e32 v62, v62, v66
	v_ashrrev_i32_e32 v63, 31, v62
	v_lshl_add_u64 v[76:77], v[62:63], 2, s[2:3]
	global_load_dwordx4 v[92:95], v[76:77], off
	v_readlane_b32 s40, v244, 48
	s_add_u32 s8, s40, s8
	v_readlane_b32 s46, v244, 49
	s_addc_u32 s9, s46, s9
	v_lshlrev_b32_e32 v0, 1, v0
	v_lshl_add_u64 v[96:97], s[8:9], 0, v[0:1]
	v_lshlrev_b64 v[80:81], 1, v[62:63]
	v_lshl_add_u64 v[64:65], v[96:97], 0, v[80:81]
	global_load_dwordx2 v[98:99], v[64:65], off
	v_and_b32_e32 v63, 0xffffffc0, v78
	v_add_u32_e32 v86, 0x400, v63
	v_lshl_add_u32 v89, s34, 11, v86
	v_add_u32_e32 v87, 0, v82
	v_or_b32_e32 v82, v89, v84
	v_ashrrev_i32_e32 v63, 31, v66
	v_ashrrev_i32_e32 v83, 31, v82
	v_lshlrev_b32_e32 v90, 1, v62
	v_lshl_add_u64 v[72:73], v[62:63], 2, s[2:3]
	v_lshlrev_b64 v[74:75], 1, v[62:63]
	v_lshlrev_b64 v[62:63], 6, v[82:83]
	v_add_u32_e32 v64, v87, v90
	ds_read2st64_b64 v[64:67], v64 offset1:66
	v_lshlrev_b32_e32 v78, 3, v79
	v_mov_b32_e32 v79, v1
	v_lshl_add_u64 v[62:63], s[54:55], 0, v[62:63]
	v_lshl_add_u64 v[100:101], v[62:63], 0, v[78:79]
	s_waitcnt lgkmcnt(0)
	v_lshlrev_b32_e32 v62, 16, v64
	v_and_b32_e32 v63, 0xffff0000, v64
	v_lshlrev_b32_e32 v64, 16, v65
	v_and_b32_e32 v65, 0xffff0000, v65
	v_add_u32_e32 v91, 0x2100, v87
	s_add_u32 s6, s40, s6
	s_addc_u32 s7, s46, s7
	s_waitcnt vmcnt(1)
	v_add_f32_e32 v54, v54, v92
	v_add_f32_e32 v55, v55, v93
	v_add_f32_e32 v56, v56, v94
	v_add_f32_e32 v57, v57, v95
	v_mul_f32_e32 v82, 0xbfb8aa3b, v54
	v_mul_f32_e32 v83, 0xbfb8aa3b, v55
	v_mul_f32_e32 v56, 0xbfb8aa3b, v56
	v_mul_f32_e32 v57, 0xbfb8aa3b, v57
	v_exp_f32_e32 v82, v82
	v_exp_f32_e32 v83, v83
	v_exp_f32_e32 v56, v56
	v_exp_f32_e32 v57, v57
	v_add_f32_e32 v82, 1.0, v82
	v_add_f32_e32 v83, 1.0, v83
	v_add_f32_e32 v85, 1.0, v56
	v_add_f32_e32 v88, 1.0, v57
	v_rcp_f32_e32 v56, v82
	v_rcp_f32_e32 v57, v83
	v_rcp_f32_e32 v82, v85
	v_rcp_f32_e32 v83, v88
	s_waitcnt vmcnt(0)
	v_lshlrev_b32_e32 v54, 16, v98
	v_and_b32_e32 v55, 0xffff0000, v98
	v_lshlrev_b32_e32 v92, 16, v99
	v_and_b32_e32 v93, 0xffff0000, v99
	v_pk_mul_f32 v[56:57], v[56:57], v[62:63]
	v_pk_mul_f32 v[62:63], v[82:83], v[64:65]
	v_pk_mul_f32 v[54:55], v[56:57], v[54:55]
	v_pk_mul_f32 v[56:57], v[62:63], v[92:93]
	v_cvt_pk_bf16_f32 v54, v54, v55
	v_cvt_pk_bf16_f32 v55, v56, v57
	global_store_dwordx2 v[100:101], v[54:55], off
	global_load_dwordx4 v[62:65], v[72:73], off offset:64
	v_lshl_add_u64 v[54:55], v[96:97], 0, v[74:75]
	global_load_dwordx2 v[92:93], v[54:55], off offset:32
	v_or_b32_e32 v88, 32, v90
	v_add_u32_e32 v54, v87, v88
	ds_read2st64_b64 v[54:57], v54 offset1:66
	v_or_b32_e32 v85, 16, v84
	v_mov_b32_e32 v83, v1
	v_lshlrev_b32_e32 v82, 9, v85
	v_lshl_add_u64 v[94:95], s[8:9], 0, v[82:83]
	s_waitcnt lgkmcnt(0)
	v_lshlrev_b32_e32 v96, 16, v54
	v_and_b32_e32 v97, 0xffff0000, v54
	v_lshlrev_b32_e32 v54, 16, v55
	v_and_b32_e32 v55, 0xffff0000, v55
	s_waitcnt vmcnt(1)
	v_add_f32_e32 v62, v58, v62
	v_add_f32_e32 v63, v59, v63
	v_add_f32_e32 v60, v60, v64
	v_add_f32_e32 v61, v61, v65
	v_mul_f32_e32 v62, 0xbfb8aa3b, v62
	v_mul_f32_e32 v63, 0xbfb8aa3b, v63
	v_mul_f32_e32 v60, 0xbfb8aa3b, v60
	v_mul_f32_e32 v61, 0xbfb8aa3b, v61
	v_exp_f32_e32 v62, v62
	v_exp_f32_e32 v63, v63
	v_exp_f32_e32 v60, v60
	v_exp_f32_e32 v61, v61
	v_add_f32_e32 v62, 1.0, v62
	v_add_f32_e32 v63, 1.0, v63
	v_add_f32_e32 v64, 1.0, v60
	v_add_f32_e32 v65, 1.0, v61
	v_rcp_f32_e32 v60, v62
	v_rcp_f32_e32 v61, v63
	v_rcp_f32_e32 v62, v64
	v_rcp_f32_e32 v63, v65
	s_waitcnt vmcnt(0)
	v_lshlrev_b32_e32 v58, 16, v92
	v_and_b32_e32 v59, 0xffff0000, v92
	v_lshlrev_b32_e32 v64, 16, v93
	v_and_b32_e32 v65, 0xffff0000, v93
	v_pk_mul_f32 v[60:61], v[60:61], v[96:97]
	v_pk_mul_f32 v[54:55], v[62:63], v[54:55]
	v_pk_mul_f32 v[58:59], v[60:61], v[58:59]
	v_pk_mul_f32 v[54:55], v[54:55], v[64:65]
	v_cvt_pk_bf16_f32 v58, v58, v59
	v_cvt_pk_bf16_f32 v59, v54, v55
	global_store_dwordx2 v[100:101], v[58:59], off offset:32
	v_lshl_add_u64 v[54:55], v[94:95], 0, v[80:81]
	global_load_dwordx4 v[62:65], v[76:77], off
	v_add_u32_e32 v58, v91, v90
	global_load_dwordx2 v[54:55], v[54:55], off
	ds_read2st64_b64 v[58:61], v58 offset1:66
	v_or_b32_e32 v92, v89, v85
	v_ashrrev_i32_e32 v93, 31, v92
	v_lshlrev_b64 v[92:93], 6, v[92:93]
	v_lshl_add_u64 v[92:93], s[54:55], 0, v[92:93]
	s_waitcnt lgkmcnt(0)
; DI unsigned pk2(float lo, float hi) { const f32x2 v = {lo, hi}; const bf16x2_t b = __builtin_convertvector(v, bf16x2_t); return __builtin_bit_cast(unsigned, b); }
; DI float bf2f(unsigned b) { return __uint_as_float(b << 16); }
; DI float sigmoid_f(float x) { return __builtin_amdgcn_rcpf(1.f + __builtin_amdgcn_exp2f(x * -1.44269504089f)); }
; DI size_t y_off(int tok, int col) { return ((size_t)(((tok >> 6) * 32 + (col >> 5)) * 64 + (tok & 63))) * 32 + (col & 31); }
; template <int NT2>
; DI void glu_prologue(const Params& p, char* lds, int l, int tile0, int tile1) {
;     ...
;     for (int tt = 0; tt < NT2; ++tt) {
;         const int tile = tt ? tile1 : tile0;
;         const char* Ys = lds + tt * 33792;
;         const bf16_t* sg = WS_PTR(const bf16_t, OFF_SG) + (size_t)tile * 64 * 256;
; #pragma unroll
;         for (int mt = 0; mt < 4; ++mt) {
;             const int tok = mt * 16 + l15;
; #pragma unroll
;             for (int nt = 0; nt < 2; ++nt) {
;                 const int n0 = wid * 32 + nt * 16 + quad * 4;
;                 const f32x4 gb = *(const f32x4*)(p.glu_b + l * 256 + n0);
;                 const u32x2 yv = *(const u32x2*)(Ys + tok * 528 + n0 * 2);
;                 const u32x2 sv = *(const u32x2*)(sg + (size_t)tok * 256 + n0);
;                 float o[4];
;                 o[0] = sigmoid_f(acc[tt][mt][nt][0] + gb[0]) * bf2f(yv[0] & 0xffffu) * bf2f(sv[0] & 0xffffu);
;                 o[1] = sigmoid_f(acc[tt][mt][nt][1] + gb[1]) * bf2f(yv[0] >> 16) * bf2f(sv[0] >> 16);
;                 o[2] = sigmoid_f(acc[tt][mt][nt][2] + gb[2]) * bf2f(yv[1] & 0xffffu) * bf2f(sv[1] & 0xffffu);
;                 o[3] = sigmoid_f(acc[tt][mt][nt][3] + gb[3]) * bf2f(yv[1] >> 16) * bf2f(sv[1] >> 16);
;                 *(u32x2*)(yo + y_off(tile * 64 + tok, 512 + n0)) = (u32x2){pk2(o[0], o[1]), pk2(o[2], o[3])};
;             }
	v_lshlrev_b32_e32 v96, 16, v58
	v_and_b32_e32 v97, 0xffff0000, v58
	v_lshlrev_b32_e32 v58, 16, v59
	v_and_b32_e32 v59, 0xffff0000, v59
	v_lshl_add_u64 v[92:93], v[92:93], 0, v[78:79]
	s_waitcnt vmcnt(1)
	v_add_f32_e32 v68, v68, v62
	v_add_f32_e32 v69, v69, v63
	s_waitcnt vmcnt(0)
	v_lshlrev_b32_e32 v62, 16, v54
	v_and_b32_e32 v63, 0xffff0000, v54
	v_add_f32_e32 v54, v70, v64
	v_add_f32_e32 v64, v71, v65
	v_mul_f32_e32 v65, 0xbfb8aa3b, v68
	v_mul_f32_e32 v68, 0xbfb8aa3b, v69
	v_mul_f32_e32 v54, 0xbfb8aa3b, v54
	v_mul_f32_e32 v64, 0xbfb8aa3b, v64
	v_exp_f32_e32 v65, v65
	v_exp_f32_e32 v68, v68
	v_exp_f32_e32 v54, v54
	v_exp_f32_e32 v64, v64
	v_add_f32_e32 v65, 1.0, v65
	v_add_f32_e32 v68, 1.0, v68
	v_add_f32_e32 v54, 1.0, v54
	v_add_f32_e32 v69, 1.0, v64
	v_rcp_f32_e32 v64, v65
	v_rcp_f32_e32 v65, v68
	v_rcp_f32_e32 v68, v54
	v_rcp_f32_e32 v69, v69
	v_lshlrev_b32_e32 v54, 16, v55
	v_and_b32_e32 v55, 0xffff0000, v55
	v_pk_mul_f32 v[64:65], v[64:65], v[96:97]
	v_pk_mul_f32 v[58:59], v[68:69], v[58:59]
	v_pk_mul_f32 v[62:63], v[64:65], v[62:63]
	v_pk_mul_f32 v[54:55], v[58:59], v[54:55]
	v_cvt_pk_bf16_f32 v58, v62, v63
	v_cvt_pk_bf16_f32 v59, v54, v55
	global_store_dwordx2 v[92:93], v[58:59], off
	global_load_dwordx4 v[68:71], v[72:73], off offset:64
	v_lshl_add_u64 v[54:55], v[94:95], 0, v[74:75]
	global_load_dwordx2 v[94:95], v[54:55], off offset:32
	v_add_u32_e32 v54, v91, v88
	ds_read2st64_b64 v[62:65], v54 offset1:66
	v_or_b32_e32 v58, 32, v84
	v_mov_b32_e32 v55, v1
	v_lshlrev_b32_e32 v54, 9, v58
	v_lshl_add_u64 v[96:97], s[8:9], 0, v[54:55]
	s_waitcnt lgkmcnt(0)
	v_lshlrev_b32_e32 v98, 16, v62
	v_and_b32_e32 v99, 0xffff0000, v62
	v_lshlrev_b32_e32 v62, 16, v63
	v_and_b32_e32 v63, 0xffff0000, v63
	s_waitcnt vmcnt(1)
	v_add_f32_e32 v59, v50, v68
	v_add_f32_e32 v68, v51, v69
	v_add_f32_e32 v52, v52, v70
	v_add_f32_e32 v53, v53, v71
	v_mul_f32_e32 v59, 0xbfb8aa3b, v59
	v_mul_f32_e32 v68, 0xbfb8aa3b, v68
	v_mul_f32_e32 v52, 0xbfb8aa3b, v52
	v_mul_f32_e32 v53, 0xbfb8aa3b, v53
	v_exp_f32_e32 v59, v59
	v_exp_f32_e32 v68, v68
	v_exp_f32_e32 v52, v52
	v_exp_f32_e32 v53, v53
	v_add_f32_e32 v59, 1.0, v59
	v_add_f32_e32 v68, 1.0, v68
	v_add_f32_e32 v69, 1.0, v52
	v_add_f32_e32 v70, 1.0, v53
	v_rcp_f32_e32 v52, v59
	v_rcp_f32_e32 v53, v68
	v_rcp_f32_e32 v68, v69
	v_rcp_f32_e32 v69, v70
	s_waitcnt vmcnt(0)
	v_lshlrev_b32_e32 v50, 16, v94
	v_and_b32_e32 v51, 0xffff0000, v94
	v_lshlrev_b32_e32 v70, 16, v95
	v_and_b32_e32 v71, 0xffff0000, v95
	v_pk_mul_f32 v[52:53], v[52:53], v[98:99]
	v_pk_mul_f32 v[62:63], v[68:69], v[62:63]
	v_pk_mul_f32 v[50:51], v[52:53], v[50:51]
	v_pk_mul_f32 v[52:53], v[62:63], v[70:71]
	v_cvt_pk_bf16_f32 v50, v50, v51
	v_cvt_pk_bf16_f32 v51, v52, v53
	global_store_dwordx2 v[92:93], v[50:51], off offset:32
	global_load_dwordx4 v[68:71], v[76:77], off
	v_lshl_add_u64 v[50:51], v[96:97], 0, v[80:81]
	global_load_dwordx2 v[62:63], v[50:51], off
	v_add_u32_e32 v59, 0x4200, v87
	v_add_u32_e32 v50, v59, v90
	ds_read2st64_b64 v[50:53], v50 offset1:66
	v_or_b32_e32 v92, v89, v58
	v_ashrrev_i32_e32 v93, 31, v92
	v_lshlrev_b64 v[92:93], 6, v[92:93]
	v_lshl_add_u64 v[92:93], s[54:55], 0, v[92:93]
	s_waitcnt lgkmcnt(0)
	v_lshlrev_b32_e32 v94, 16, v50
	v_and_b32_e32 v95, 0xffff0000, v50
	v_lshlrev_b32_e32 v50, 16, v51
	v_and_b32_e32 v51, 0xffff0000, v51
	v_lshl_add_u64 v[92:93], v[92:93], 0, v[78:79]
	v_add_u32_e32 v87, 0x6300, v87
	s_waitcnt vmcnt(1)
	v_add_f32_e32 v68, v46, v68
	v_add_f32_e32 v69, v47, v69
	v_add_f32_e32 v48, v48, v70
	v_add_f32_e32 v49, v49, v71
	s_waitcnt vmcnt(0)
	v_lshlrev_b32_e32 v46, 16, v62
	v_and_b32_e32 v47, 0xffff0000, v62
	v_mul_f32_e32 v62, 0xbfb8aa3b, v68
	v_mul_f32_e32 v68, 0xbfb8aa3b, v69
	v_mul_f32_e32 v48, 0xbfb8aa3b, v48
	v_mul_f32_e32 v49, 0xbfb8aa3b, v49
	v_exp_f32_e32 v62, v62
	v_exp_f32_e32 v68, v68
	v_exp_f32_e32 v48, v48
	v_exp_f32_e32 v49, v49
	v_add_f32_e32 v62, 1.0, v62
	v_add_f32_e32 v68, 1.0, v68
	v_add_f32_e32 v69, 1.0, v48
	v_add_f32_e32 v70, 1.0, v49
	v_rcp_f32_e32 v48, v62
	v_rcp_f32_e32 v49, v68
	v_rcp_f32_e32 v68, v69
	v_rcp_f32_e32 v69, v70
	v_lshlrev_b32_e32 v62, 16, v63
	v_and_b32_e32 v63, 0xffff0000, v63
	v_pk_mul_f32 v[48:49], v[48:49], v[94:95]
	v_pk_mul_f32 v[50:51], v[68:69], v[50:51]
	v_pk_mul_f32 v[46:47], v[48:49], v[46:47]
	v_pk_mul_f32 v[48:49], v[50:51], v[62:63]
	v_cvt_pk_bf16_f32 v46, v46, v47
	v_cvt_pk_bf16_f32 v47, v48, v49
	global_store_dwordx2 v[92:93], v[46:47], off
	global_load_dwordx4 v[68:71], v[72:73], off offset:64
	v_lshl_add_u64 v[46:47], v[96:97], 0, v[74:75]
	global_load_dwordx2 v[62:63], v[46:47], off offset:32
	v_add_u32_e32 v46, v59, v88
	ds_read2st64_b64 v[46:49], v46 offset1:66
	v_or_b32_e32 v59, 48, v84
	v_mov_b32_e32 v51, v1
	v_lshlrev_b32_e32 v50, 9, v59
	v_lshl_add_u64 v[94:95], s[8:9], 0, v[50:51]
	s_waitcnt lgkmcnt(0)
	v_lshlrev_b32_e32 v96, 16, v46
	v_and_b32_e32 v97, 0xffff0000, v46
	v_lshlrev_b32_e32 v46, 16, v47
	v_and_b32_e32 v47, 0xffff0000, v47
	s_waitcnt vmcnt(1)
	v_add_f32_e32 v68, v42, v68
	v_add_f32_e32 v69, v43, v69
	v_add_f32_e32 v44, v44, v70
	v_add_f32_e32 v45, v45, v71
	s_waitcnt vmcnt(0)
; DI unsigned pk2(float lo, float hi) { const f32x2 v = {lo, hi}; const bf16x2_t b = __builtin_convertvector(v, bf16x2_t); return __builtin_bit_cast(unsigned, b); }
; DI float bf2f(unsigned b) { return __uint_as_float(b << 16); }
; DI float sigmoid_f(float x) { return __builtin_amdgcn_rcpf(1.f + __builtin_amdgcn_exp2f(x * -1.44269504089f)); }
; DI size_t y_off(int tok, int col) { return ((size_t)(((tok >> 6) * 32 + (col >> 5)) * 64 + (tok & 63))) * 32 + (col & 31); }
; template <int NT2>
; DI void glu_prologue(const Params& p, char* lds, int l, int tile0, int tile1) {
;     ...
;     for (int tt = 0; tt < NT2; ++tt) {
;         const int tile = tt ? tile1 : tile0;
;         const char* Ys = lds + tt * 33792;
;         const bf16_t* sg = WS_PTR(const bf16_t, OFF_SG) + (size_t)tile * 64 * 256;
; #pragma unroll
;         for (int mt = 0; mt < 4; ++mt) {
;             const int tok = mt * 16 + l15;
; #pragma unroll
;             for (int nt = 0; nt < 2; ++nt) {
;                 const int n0 = wid * 32 + nt * 16 + quad * 4;
;                 const f32x4 gb = *(const f32x4*)(p.glu_b + l * 256 + n0);
;                 const u32x2 yv = *(const u32x2*)(Ys + tok * 528 + n0 * 2);
;                 const u32x2 sv = *(const u32x2*)(sg + (size_t)tok * 256 + n0);
;                 float o[4];
;                 o[0] = sigmoid_f(acc[tt][mt][nt][0] + gb[0]) * bf2f(yv[0] & 0xffffu) * bf2f(sv[0] & 0xffffu);
;                 o[1] = sigmoid_f(acc[tt][mt][nt][1] + gb[1]) * bf2f(yv[0] >> 16) * bf2f(sv[0] >> 16);
;                 o[2] = sigmoid_f(acc[tt][mt][nt][2] + gb[2]) * bf2f(yv[1] & 0xffffu) * bf2f(sv[1] & 0xffffu);
;                 o[3] = sigmoid_f(acc[tt][mt][nt][3] + gb[3]) * bf2f(yv[1] >> 16) * bf2f(sv[1] >> 16);
;                 *(u32x2*)(yo + y_off(tile * 64 + tok, 512 + n0)) = (u32x2){pk2(o[0], o[1]), pk2(o[2], o[3])};
;             }
	v_lshlrev_b32_e32 v42, 16, v62
	v_and_b32_e32 v43, 0xffff0000, v62
	v_mul_f32_e32 v62, 0xbfb8aa3b, v68
	v_mul_f32_e32 v68, 0xbfb8aa3b, v69
	v_mul_f32_e32 v44, 0xbfb8aa3b, v44
	v_mul_f32_e32 v45, 0xbfb8aa3b, v45
	v_exp_f32_e32 v62, v62
	v_exp_f32_e32 v68, v68
	v_exp_f32_e32 v44, v44
	v_exp_f32_e32 v45, v45
	v_add_f32_e32 v62, 1.0, v62
	v_add_f32_e32 v68, 1.0, v68
	v_add_f32_e32 v69, 1.0, v44
	v_add_f32_e32 v70, 1.0, v45
	v_rcp_f32_e32 v44, v62
	v_rcp_f32_e32 v45, v68
	v_rcp_f32_e32 v68, v69
	v_rcp_f32_e32 v69, v70
	v_lshlrev_b32_e32 v62, 16, v63
	v_and_b32_e32 v63, 0xffff0000, v63
	v_pk_mul_f32 v[44:45], v[44:45], v[96:97]
	v_pk_mul_f32 v[46:47], v[68:69], v[46:47]
	v_pk_mul_f32 v[42:43], v[44:45], v[42:43]
	v_pk_mul_f32 v[44:45], v[46:47], v[62:63]
	v_cvt_pk_bf16_f32 v42, v42, v43
	v_cvt_pk_bf16_f32 v43, v44, v45
	global_store_dwordx2 v[92:93], v[42:43], off offset:32
	global_load_dwordx4 v[68:71], v[76:77], off
	v_lshl_add_u64 v[42:43], v[94:95], 0, v[80:81]
	global_load_dwordx2 v[46:47], v[42:43], off
	v_add_u32_e32 v42, v87, v90
	ds_read2st64_b64 v[42:45], v42 offset1:66
	v_or_b32_e32 v62, v89, v59
	v_ashrrev_i32_e32 v63, 31, v62
	v_lshlrev_b64 v[62:63], 6, v[62:63]
	v_lshl_add_u64 v[62:63], s[54:55], 0, v[62:63]
	s_waitcnt lgkmcnt(0)
	v_lshlrev_b32_e32 v90, 16, v42
	v_and_b32_e32 v91, 0xffff0000, v42
	v_lshlrev_b32_e32 v42, 16, v43
	v_and_b32_e32 v43, 0xffff0000, v43
	v_lshl_add_u64 v[62:63], v[62:63], 0, v[78:79]
	s_waitcnt vmcnt(1)
	v_add_f32_e32 v68, v38, v68
	v_add_f32_e32 v69, v39, v69
	v_add_f32_e32 v40, v40, v70
	v_add_f32_e32 v41, v41, v71
	s_waitcnt vmcnt(0)
	v_lshlrev_b32_e32 v38, 16, v46
	v_and_b32_e32 v39, 0xffff0000, v46
	v_mul_f32_e32 v46, 0xbfb8aa3b, v68
	v_mul_f32_e32 v68, 0xbfb8aa3b, v69
	v_mul_f32_e32 v40, 0xbfb8aa3b, v40
	v_mul_f32_e32 v41, 0xbfb8aa3b, v41
	v_exp_f32_e32 v46, v46
	v_exp_f32_e32 v68, v68
	v_exp_f32_e32 v40, v40
	v_exp_f32_e32 v41, v41
	v_add_f32_e32 v46, 1.0, v46
	v_add_f32_e32 v68, 1.0, v68
	v_add_f32_e32 v69, 1.0, v40
	v_add_f32_e32 v70, 1.0, v41
	v_rcp_f32_e32 v40, v46
	v_rcp_f32_e32 v41, v68
	v_rcp_f32_e32 v68, v69
	v_rcp_f32_e32 v69, v70
	v_lshlrev_b32_e32 v46, 16, v47
	v_and_b32_e32 v47, 0xffff0000, v47
	v_pk_mul_f32 v[40:41], v[40:41], v[90:91]
	v_pk_mul_f32 v[42:43], v[68:69], v[42:43]
	v_pk_mul_f32 v[38:39], v[40:41], v[38:39]
	v_pk_mul_f32 v[40:41], v[42:43], v[46:47]
	v_cvt_pk_bf16_f32 v38, v38, v39
	v_cvt_pk_bf16_f32 v39, v40, v41
	global_store_dwordx2 v[62:63], v[38:39], off
	global_load_dwordx4 v[68:71], v[72:73], off offset:64
	v_lshl_add_u64 v[38:39], v[94:95], 0, v[74:75]
	global_load_dwordx2 v[42:43], v[38:39], off offset:32
	v_lshl_add_u64 v[46:47], s[6:7], 0, v[0:1]
	v_add_u32_e32 v38, v87, v88
	ds_read2st64_b64 v[38:41], v38 offset1:66
	s_waitcnt lgkmcnt(0)
	v_lshlrev_b32_e32 v88, 16, v38
	v_and_b32_e32 v89, 0xffff0000, v38
	v_lshlrev_b32_e32 v38, 16, v39
	v_and_b32_e32 v39, 0xffff0000, v39
	s_waitcnt vmcnt(1)
	v_add_f32_e32 v0, v30, v68
	v_add_f32_e32 v68, v31, v69
	v_add_f32_e32 v32, v32, v70
	v_add_f32_e32 v33, v33, v71
	s_waitcnt vmcnt(0)
	v_lshlrev_b32_e32 v30, 16, v42
	v_and_b32_e32 v31, 0xffff0000, v42
	v_mul_f32_e32 v0, 0xbfb8aa3b, v0
	v_mul_f32_e32 v42, 0xbfb8aa3b, v68
	v_mul_f32_e32 v32, 0xbfb8aa3b, v32
	v_mul_f32_e32 v33, 0xbfb8aa3b, v33
	v_exp_f32_e32 v0, v0
	v_exp_f32_e32 v42, v42
	v_exp_f32_e32 v32, v32
	v_exp_f32_e32 v33, v33
	v_add_f32_e32 v0, 1.0, v0
	v_add_f32_e32 v42, 1.0, v42
	v_add_f32_e32 v68, 1.0, v32
	v_add_f32_e32 v69, 1.0, v33
	v_rcp_f32_e32 v32, v0
	v_rcp_f32_e32 v33, v42
	v_rcp_f32_e32 v68, v68
	v_rcp_f32_e32 v69, v69
	v_lshlrev_b32_e32 v42, 16, v43
	v_and_b32_e32 v43, 0xffff0000, v43
	v_pk_mul_f32 v[32:33], v[32:33], v[88:89]
	v_pk_mul_f32 v[38:39], v[68:69], v[38:39]
	v_pk_mul_f32 v[30:31], v[32:33], v[30:31]
	v_pk_mul_f32 v[32:33], v[38:39], v[42:43]
	v_cvt_pk_bf16_f32 v30, v30, v31
	v_cvt_pk_bf16_f32 v31, v32, v33
	global_store_dwordx2 v[62:63], v[30:31], off offset:32
	global_load_dwordx4 v[30:33], v[76:77], off
	v_lshl_add_u64 v[38:39], v[46:47], 0, v[80:81]
	global_load_dwordx2 v[38:39], v[38:39], off
	v_lshl_add_u32 v0, s48, 11, v86
	v_or_b32_e32 v42, v0, v84
	v_ashrrev_i32_e32 v43, 31, v42
	v_lshlrev_b32_e32 v62, 16, v66
	v_and_b32_e32 v63, 0xffff0000, v66
	v_lshlrev_b32_e32 v66, 16, v67
	v_and_b32_e32 v67, 0xffff0000, v67
	v_lshlrev_b64 v[42:43], 6, v[42:43]
	v_lshl_add_u64 v[42:43], s[54:55], 0, v[42:43]
	v_lshl_add_u64 v[42:43], v[42:43], 0, v[78:79]
	s_waitcnt vmcnt(1)
	v_add_f32_e32 v34, v34, v30
	v_add_f32_e32 v35, v35, v31
	v_add_f32_e32 v32, v36, v32
	v_add_f32_e32 v33, v37, v33
	v_mul_f32_e32 v34, 0xbfb8aa3b, v34
	v_mul_f32_e32 v35, 0xbfb8aa3b, v35
	v_mul_f32_e32 v32, 0xbfb8aa3b, v32
	v_mul_f32_e32 v33, 0xbfb8aa3b, v33
	v_exp_f32_e32 v34, v34
	v_exp_f32_e32 v35, v35
	v_exp_f32_e32 v32, v32
	v_exp_f32_e32 v33, v33
	v_add_f32_e32 v34, 1.0, v34
	v_add_f32_e32 v35, 1.0, v35
	v_add_f32_e32 v36, 1.0, v32
	v_add_f32_e32 v37, 1.0, v33
	v_rcp_f32_e32 v32, v34
	v_rcp_f32_e32 v33, v35
	v_rcp_f32_e32 v34, v36
	v_rcp_f32_e32 v35, v37
	s_waitcnt vmcnt(0)
	v_lshlrev_b32_e32 v30, 16, v38
	v_and_b32_e32 v31, 0xffff0000, v38
	v_lshlrev_b32_e32 v36, 16, v39
	v_and_b32_e32 v37, 0xffff0000, v39
	v_pk_mul_f32 v[32:33], v[32:33], v[62:63]
	v_pk_mul_f32 v[34:35], v[34:35], v[66:67]
	v_pk_mul_f32 v[30:31], v[32:33], v[30:31]
	v_pk_mul_f32 v[32:33], v[34:35], v[36:37]
	v_cvt_pk_bf16_f32 v30, v30, v31
	v_cvt_pk_bf16_f32 v31, v32, v33
	global_store_dwordx2 v[42:43], v[30:31], off
	global_load_dwordx4 v[30:33], v[72:73], off offset:64
	v_lshl_add_u64 v[34:35], v[46:47], 0, v[74:75]
	global_load_dwordx2 v[34:35], v[34:35], off offset:32
	v_lshlrev_b32_e32 v38, 16, v56
	v_and_b32_e32 v39, 0xffff0000, v56
	v_lshlrev_b32_e32 v46, 16, v57
	v_and_b32_e32 v47, 0xffff0000, v57
	v_lshl_add_u64 v[36:37], s[6:7], 0, v[82:83]
	s_waitcnt vmcnt(1)
; DI unsigned pk2(float lo, float hi) { const f32x2 v = {lo, hi}; const bf16x2_t b = __builtin_convertvector(v, bf16x2_t); return __builtin_bit_cast(unsigned, b); }
; DI float bf2f(unsigned b) { return __uint_as_float(b << 16); }
; DI float sigmoid_f(float x) { return __builtin_amdgcn_rcpf(1.f + __builtin_amdgcn_exp2f(x * -1.44269504089f)); }
; DI size_t y_off(int tok, int col) { return ((size_t)(((tok >> 6) * 32 + (col >> 5)) * 64 + (tok & 63))) * 32 + (col & 31); }
; template <int NT2>
; DI void glu_prologue(const Params& p, char* lds, int l, int tile0, int tile1) {
;     ...
;     for (int tt = 0; tt < NT2; ++tt) {
;         const int tile = tt ? tile1 : tile0;
;         const char* Ys = lds + tt * 33792;
;         const bf16_t* sg = WS_PTR(const bf16_t, OFF_SG) + (size_t)tile * 64 * 256;
; #pragma unroll
;         for (int mt = 0; mt < 4; ++mt) {
;             const int tok = mt * 16 + l15;
; #pragma unroll
;             for (int nt = 0; nt < 2; ++nt) {
;                 const int n0 = wid * 32 + nt * 16 + quad * 4;
;                 const f32x4 gb = *(const f32x4*)(p.glu_b + l * 256 + n0);
;                 const u32x2 yv = *(const u32x2*)(Ys + tok * 528 + n0 * 2);
;                 const u32x2 sv = *(const u32x2*)(sg + (size_t)tok * 256 + n0);
;                 float o[4];
;                 o[0] = sigmoid_f(acc[tt][mt][nt][0] + gb[0]) * bf2f(yv[0] & 0xffffu) * bf2f(sv[0] & 0xffffu);
;                 o[1] = sigmoid_f(acc[tt][mt][nt][1] + gb[1]) * bf2f(yv[0] >> 16) * bf2f(sv[0] >> 16);
;                 o[2] = sigmoid_f(acc[tt][mt][nt][2] + gb[2]) * bf2f(yv[1] & 0xffffu) * bf2f(sv[1] & 0xffffu);
;                 o[3] = sigmoid_f(acc[tt][mt][nt][3] + gb[3]) * bf2f(yv[1] >> 16) * bf2f(sv[1] >> 16);
;                 *(u32x2*)(yo + y_off(tile * 64 + tok, 512 + n0)) = (u32x2){pk2(o[0], o[1]), pk2(o[2], o[3])};
;             }
	v_add_f32_e32 v30, v26, v30
	v_add_f32_e32 v31, v27, v31
	v_add_f32_e32 v28, v28, v32
	v_add_f32_e32 v29, v29, v33
	v_mul_f32_e32 v30, 0xbfb8aa3b, v30
	v_mul_f32_e32 v31, 0xbfb8aa3b, v31
	v_mul_f32_e32 v28, 0xbfb8aa3b, v28
	v_mul_f32_e32 v29, 0xbfb8aa3b, v29
	v_exp_f32_e32 v30, v30
	v_exp_f32_e32 v31, v31
	v_exp_f32_e32 v28, v28
	v_exp_f32_e32 v29, v29
	v_add_f32_e32 v30, 1.0, v30
	v_add_f32_e32 v31, 1.0, v31
	v_add_f32_e32 v32, 1.0, v28
	v_add_f32_e32 v33, 1.0, v29
	v_rcp_f32_e32 v28, v30
	v_rcp_f32_e32 v29, v31
	v_rcp_f32_e32 v30, v32
	v_rcp_f32_e32 v31, v33
	s_waitcnt vmcnt(0)
	v_lshlrev_b32_e32 v26, 16, v34
	v_and_b32_e32 v27, 0xffff0000, v34
	v_lshlrev_b32_e32 v32, 16, v35
	v_and_b32_e32 v33, 0xffff0000, v35
	v_pk_mul_f32 v[28:29], v[28:29], v[38:39]
	v_pk_mul_f32 v[30:31], v[30:31], v[46:47]
	v_pk_mul_f32 v[26:27], v[28:29], v[26:27]
	v_pk_mul_f32 v[28:29], v[30:31], v[32:33]
	v_cvt_pk_bf16_f32 v26, v26, v27
	v_cvt_pk_bf16_f32 v27, v28, v29
	global_store_dwordx2 v[42:43], v[26:27], off offset:32
	global_load_dwordx4 v[26:29], v[76:77], off
	v_lshl_add_u64 v[30:31], v[36:37], 0, v[80:81]
	global_load_dwordx2 v[30:31], v[30:31], off
	v_or_b32_e32 v32, v0, v85
	v_ashrrev_i32_e32 v33, 31, v32
	v_lshlrev_b32_e32 v34, 16, v60
	v_and_b32_e32 v35, 0xffff0000, v60
	v_lshlrev_b32_e32 v38, 16, v61
	v_and_b32_e32 v39, 0xffff0000, v61
	v_lshlrev_b64 v[32:33], 6, v[32:33]
	v_lshl_add_u64 v[32:33], s[54:55], 0, v[32:33]
	v_lshl_add_u64 v[32:33], v[32:33], 0, v[78:79]
	s_waitcnt vmcnt(1)
	v_add_f32_e32 v26, v22, v26
	v_add_f32_e32 v27, v23, v27
	v_add_f32_e32 v24, v24, v28
	v_add_f32_e32 v25, v25, v29
	v_mul_f32_e32 v26, 0xbfb8aa3b, v26
	v_mul_f32_e32 v27, 0xbfb8aa3b, v27
	v_mul_f32_e32 v24, 0xbfb8aa3b, v24
	v_mul_f32_e32 v25, 0xbfb8aa3b, v25
	v_exp_f32_e32 v26, v26
	v_exp_f32_e32 v27, v27
	v_exp_f32_e32 v24, v24
	v_exp_f32_e32 v25, v25
	v_add_f32_e32 v26, 1.0, v26
	v_add_f32_e32 v27, 1.0, v27
	v_add_f32_e32 v28, 1.0, v24
	v_add_f32_e32 v29, 1.0, v25
	v_rcp_f32_e32 v24, v26
	v_rcp_f32_e32 v25, v27
	v_rcp_f32_e32 v26, v28
	v_rcp_f32_e32 v27, v29
	s_waitcnt vmcnt(0)
	v_lshlrev_b32_e32 v22, 16, v30
	v_and_b32_e32 v23, 0xffff0000, v30
	v_lshlrev_b32_e32 v28, 16, v31
	v_and_b32_e32 v29, 0xffff0000, v31
	v_pk_mul_f32 v[24:25], v[24:25], v[34:35]
	v_pk_mul_f32 v[26:27], v[26:27], v[38:39]
	v_pk_mul_f32 v[22:23], v[24:25], v[22:23]
	v_pk_mul_f32 v[24:25], v[26:27], v[28:29]
	v_cvt_pk_bf16_f32 v22, v22, v23
	v_cvt_pk_bf16_f32 v23, v24, v25
	global_store_dwordx2 v[32:33], v[22:23], off
	global_load_dwordx4 v[22:25], v[72:73], off offset:64
	v_lshl_add_u64 v[26:27], v[36:37], 0, v[74:75]
	global_load_dwordx2 v[26:27], v[26:27], off offset:32
	v_lshlrev_b32_e32 v30, 16, v64
	v_and_b32_e32 v31, 0xffff0000, v64
	v_lshlrev_b32_e32 v34, 16, v65
	v_and_b32_e32 v35, 0xffff0000, v65
	v_lshl_add_u64 v[28:29], s[6:7], 0, v[54:55]
	s_waitcnt vmcnt(1)
	v_add_f32_e32 v22, v18, v22
	v_add_f32_e32 v23, v19, v23
	v_add_f32_e32 v20, v20, v24
	v_add_f32_e32 v21, v21, v25
	v_mul_f32_e32 v22, 0xbfb8aa3b, v22
	v_mul_f32_e32 v23, 0xbfb8aa3b, v23
	v_mul_f32_e32 v20, 0xbfb8aa3b, v20
	v_mul_f32_e32 v21, 0xbfb8aa3b, v21
	v_exp_f32_e32 v22, v22
	v_exp_f32_e32 v23, v23
	v_exp_f32_e32 v20, v20
	v_exp_f32_e32 v21, v21
	v_add_f32_e32 v22, 1.0, v22
	v_add_f32_e32 v23, 1.0, v23
	v_add_f32_e32 v24, 1.0, v20
	v_add_f32_e32 v25, 1.0, v21
	v_rcp_f32_e32 v20, v22
	v_rcp_f32_e32 v21, v23
	v_rcp_f32_e32 v22, v24
	v_rcp_f32_e32 v23, v25
	s_waitcnt vmcnt(0)
	v_lshlrev_b32_e32 v18, 16, v26
	v_and_b32_e32 v19, 0xffff0000, v26
	v_lshlrev_b32_e32 v24, 16, v27
	v_and_b32_e32 v25, 0xffff0000, v27
	v_pk_mul_f32 v[20:21], v[20:21], v[30:31]
	v_pk_mul_f32 v[22:23], v[22:23], v[34:35]
	v_pk_mul_f32 v[18:19], v[20:21], v[18:19]
	v_pk_mul_f32 v[20:21], v[22:23], v[24:25]
	v_cvt_pk_bf16_f32 v18, v18, v19
	v_cvt_pk_bf16_f32 v19, v20, v21
	global_store_dwordx2 v[32:33], v[18:19], off offset:32
	global_load_dwordx4 v[18:21], v[76:77], off
	v_lshl_add_u64 v[22:23], v[28:29], 0, v[80:81]
	global_load_dwordx2 v[22:23], v[22:23], off
	v_or_b32_e32 v24, v0, v58
	v_ashrrev_i32_e32 v25, 31, v24
	v_lshlrev_b32_e32 v26, 16, v52
	v_and_b32_e32 v27, 0xffff0000, v52
	v_lshlrev_b32_e32 v30, 16, v53
	v_and_b32_e32 v31, 0xffff0000, v53
	v_lshlrev_b64 v[24:25], 6, v[24:25]
	v_lshl_add_u64 v[24:25], s[54:55], 0, v[24:25]
	v_lshl_add_u64 v[24:25], v[24:25], 0, v[78:79]
	s_waitcnt vmcnt(1)
	v_add_f32_e32 v18, v14, v18
	v_add_f32_e32 v19, v15, v19
	v_add_f32_e32 v16, v16, v20
	v_add_f32_e32 v17, v17, v21
	v_mul_f32_e32 v18, 0xbfb8aa3b, v18
	v_mul_f32_e32 v19, 0xbfb8aa3b, v19
	v_mul_f32_e32 v16, 0xbfb8aa3b, v16
	v_mul_f32_e32 v17, 0xbfb8aa3b, v17
	v_exp_f32_e32 v18, v18
	v_exp_f32_e32 v19, v19
	v_exp_f32_e32 v16, v16
	v_exp_f32_e32 v17, v17
	v_add_f32_e32 v18, 1.0, v18
	v_add_f32_e32 v19, 1.0, v19
	v_add_f32_e32 v20, 1.0, v16
	v_add_f32_e32 v21, 1.0, v17
	v_rcp_f32_e32 v16, v18
	v_rcp_f32_e32 v17, v19
	v_rcp_f32_e32 v18, v20
	v_rcp_f32_e32 v19, v21
	s_waitcnt vmcnt(0)
; DI unsigned pk2(float lo, float hi) { const f32x2 v = {lo, hi}; const bf16x2_t b = __builtin_convertvector(v, bf16x2_t); return __builtin_bit_cast(unsigned, b); }
; DI float bf2f(unsigned b) { return __uint_as_float(b << 16); }
; DI float sigmoid_f(float x) { return __builtin_amdgcn_rcpf(1.f + __builtin_amdgcn_exp2f(x * -1.44269504089f)); }
; template <int N> DI void wait_vm() { asm volatile("s_waitcnt vmcnt(%0)" ::"n"(N) : "memory"); }
; DI size_t y_off(int tok, int col) { return ((size_t)(((tok >> 6) * 32 + (col >> 5)) * 64 + (tok & 63))) * 32 + (col & 31); }
; template <int NT2>
; DI void glu_prologue(const Params& p, char* lds, int l, int tile0, int tile1) {
;     ...
;     for (int tt = 0; tt < NT2; ++tt) {
;         const int tile = tt ? tile1 : tile0;
;         const char* Ys = lds + tt * 33792;
;         const bf16_t* sg = WS_PTR(const bf16_t, OFF_SG) + (size_t)tile * 64 * 256;
; #pragma unroll
;         for (int mt = 0; mt < 4; ++mt) {
;             const int tok = mt * 16 + l15;
; #pragma unroll
;             for (int nt = 0; nt < 2; ++nt) {
;                 const int n0 = wid * 32 + nt * 16 + quad * 4;
;                 const f32x4 gb = *(const f32x4*)(p.glu_b + l * 256 + n0);
;                 const u32x2 yv = *(const u32x2*)(Ys + tok * 528 + n0 * 2);
;                 const u32x2 sv = *(const u32x2*)(sg + (size_t)tok * 256 + n0);
;                 float o[4];
;                 o[0] = sigmoid_f(acc[tt][mt][nt][0] + gb[0]) * bf2f(yv[0] & 0xffffu) * bf2f(sv[0] & 0xffffu);
;                 o[1] = sigmoid_f(acc[tt][mt][nt][1] + gb[1]) * bf2f(yv[0] >> 16) * bf2f(sv[0] >> 16);
;                 o[2] = sigmoid_f(acc[tt][mt][nt][2] + gb[2]) * bf2f(yv[1] & 0xffffu) * bf2f(sv[1] & 0xffffu);
;                 o[3] = sigmoid_f(acc[tt][mt][nt][3] + gb[3]) * bf2f(yv[1] >> 16) * bf2f(sv[1] >> 16);
;                 *(u32x2*)(yo + y_off(tile * 64 + tok, 512 + n0)) = (u32x2){pk2(o[0], o[1]), pk2(o[2], o[3])};
;             }
;         }
;     }
;     wait_vm<0>();
	v_lshlrev_b32_e32 v14, 16, v22
	v_and_b32_e32 v15, 0xffff0000, v22
	v_lshlrev_b32_e32 v20, 16, v23
	v_and_b32_e32 v21, 0xffff0000, v23
	v_pk_mul_f32 v[16:17], v[16:17], v[26:27]
	v_pk_mul_f32 v[18:19], v[18:19], v[30:31]
	v_pk_mul_f32 v[14:15], v[16:17], v[14:15]
	v_pk_mul_f32 v[16:17], v[18:19], v[20:21]
	v_cvt_pk_bf16_f32 v14, v14, v15
	v_cvt_pk_bf16_f32 v15, v16, v17
	global_store_dwordx2 v[24:25], v[14:15], off
	global_load_dwordx4 v[14:17], v[72:73], off offset:64
	v_lshl_add_u64 v[18:19], v[28:29], 0, v[74:75]
	global_load_dwordx2 v[18:19], v[18:19], off offset:32
	v_lshlrev_b32_e32 v22, 16, v48
	v_and_b32_e32 v23, 0xffff0000, v48
	v_lshlrev_b32_e32 v26, 16, v49
	v_and_b32_e32 v27, 0xffff0000, v49
	v_lshl_add_u64 v[20:21], s[6:7], 0, v[50:51]
	s_waitcnt vmcnt(1)
	v_add_f32_e32 v14, v2, v14
	v_add_f32_e32 v15, v3, v15
	v_add_f32_e32 v4, v4, v16
	v_add_f32_e32 v5, v5, v17
	v_mul_f32_e32 v14, 0xbfb8aa3b, v14
	v_mul_f32_e32 v15, 0xbfb8aa3b, v15
	v_mul_f32_e32 v4, 0xbfb8aa3b, v4
	v_mul_f32_e32 v5, 0xbfb8aa3b, v5
	v_exp_f32_e32 v14, v14
	v_exp_f32_e32 v15, v15
	v_exp_f32_e32 v4, v4
	v_exp_f32_e32 v5, v5
	v_add_f32_e32 v14, 1.0, v14
	v_add_f32_e32 v15, 1.0, v15
	v_add_f32_e32 v16, 1.0, v4
	v_add_f32_e32 v17, 1.0, v5
	v_rcp_f32_e32 v4, v14
	v_rcp_f32_e32 v5, v15
	v_rcp_f32_e32 v14, v16
	v_rcp_f32_e32 v15, v17
	s_waitcnt vmcnt(0)
	v_lshlrev_b32_e32 v2, 16, v18
	v_and_b32_e32 v3, 0xffff0000, v18
	v_lshlrev_b32_e32 v16, 16, v19
	v_and_b32_e32 v17, 0xffff0000, v19
	v_pk_mul_f32 v[4:5], v[4:5], v[22:23]
	v_pk_mul_f32 v[14:15], v[14:15], v[26:27]
	v_pk_mul_f32 v[2:3], v[4:5], v[2:3]
	v_pk_mul_f32 v[4:5], v[14:15], v[16:17]
	v_cvt_pk_bf16_f32 v2, v2, v3
	v_cvt_pk_bf16_f32 v3, v4, v5
	global_store_dwordx2 v[24:25], v[2:3], off offset:32
	global_load_dwordx4 v[2:5], v[76:77], off
	v_lshl_add_u64 v[14:15], v[20:21], 0, v[80:81]
	global_load_dwordx2 v[14:15], v[14:15], off
	v_or_b32_e32 v16, v0, v59
	v_ashrrev_i32_e32 v17, 31, v16
	v_lshlrev_b32_e32 v18, 16, v44
	v_and_b32_e32 v19, 0xffff0000, v44
	v_lshlrev_b32_e32 v22, 16, v45
	v_and_b32_e32 v23, 0xffff0000, v45
	v_lshlrev_b64 v[16:17], 6, v[16:17]
	v_lshl_add_u64 v[16:17], s[54:55], 0, v[16:17]
	v_lshl_add_u64 v[16:17], v[16:17], 0, v[78:79]
	s_waitcnt vmcnt(1)
	v_add_f32_e32 v0, v10, v2
	v_add_f32_e32 v10, v11, v3
	v_add_f32_e32 v4, v12, v4
	v_add_f32_e32 v5, v13, v5
	v_mul_f32_e32 v0, 0xbfb8aa3b, v0
	v_mul_f32_e32 v10, 0xbfb8aa3b, v10
	v_mul_f32_e32 v4, 0xbfb8aa3b, v4
	v_mul_f32_e32 v5, 0xbfb8aa3b, v5
	v_exp_f32_e32 v0, v0
	v_exp_f32_e32 v10, v10
	v_exp_f32_e32 v4, v4
	v_exp_f32_e32 v5, v5
	v_add_f32_e32 v0, 1.0, v0
	v_add_f32_e32 v10, 1.0, v10
	v_add_f32_e32 v11, 1.0, v4
	v_add_f32_e32 v12, 1.0, v5
	v_rcp_f32_e32 v4, v0
	v_rcp_f32_e32 v5, v10
	v_rcp_f32_e32 v10, v11
	v_rcp_f32_e32 v11, v12
	s_waitcnt vmcnt(0)
	v_lshlrev_b32_e32 v2, 16, v14
	v_and_b32_e32 v3, 0xffff0000, v14
	v_lshlrev_b32_e32 v12, 16, v15
	v_and_b32_e32 v13, 0xffff0000, v15
	v_pk_mul_f32 v[4:5], v[4:5], v[18:19]
	v_pk_mul_f32 v[10:11], v[10:11], v[22:23]
	v_pk_mul_f32 v[2:3], v[4:5], v[2:3]
	v_pk_mul_f32 v[4:5], v[10:11], v[12:13]
	v_cvt_pk_bf16_f32 v2, v2, v3
	v_cvt_pk_bf16_f32 v3, v4, v5
	global_store_dwordx2 v[16:17], v[2:3], off
	global_load_dwordx4 v[2:5], v[72:73], off offset:64
	v_lshl_add_u64 v[10:11], v[20:21], 0, v[74:75]
	global_load_dwordx2 v[10:11], v[10:11], off offset:32
	v_lshlrev_b32_e32 v12, 16, v40
	v_and_b32_e32 v13, 0xffff0000, v40
	v_lshlrev_b32_e32 v14, 16, v41
	v_and_b32_e32 v15, 0xffff0000, v41
	s_waitcnt vmcnt(1)
	v_add_f32_e32 v0, v6, v2
	v_add_f32_e32 v6, v7, v3
	v_add_f32_e32 v4, v8, v4
	v_add_f32_e32 v5, v9, v5
	v_mul_f32_e32 v0, 0xbfb8aa3b, v0
	v_mul_f32_e32 v6, 0xbfb8aa3b, v6
	v_mul_f32_e32 v4, 0xbfb8aa3b, v4
	v_mul_f32_e32 v5, 0xbfb8aa3b, v5
	v_exp_f32_e32 v0, v0
	v_exp_f32_e32 v6, v6
	v_exp_f32_e32 v4, v4
	v_exp_f32_e32 v5, v5
	v_add_f32_e32 v0, 1.0, v0
	v_add_f32_e32 v6, 1.0, v6
	v_add_f32_e32 v7, 1.0, v4
	v_add_f32_e32 v8, 1.0, v5
	v_rcp_f32_e32 v4, v0
	v_rcp_f32_e32 v5, v6
	v_rcp_f32_e32 v6, v7
	v_rcp_f32_e32 v7, v8
	s_waitcnt vmcnt(0)
	v_lshlrev_b32_e32 v2, 16, v10
	v_and_b32_e32 v3, 0xffff0000, v10
	v_lshlrev_b32_e32 v8, 16, v11
	v_and_b32_e32 v9, 0xffff0000, v11
	v_pk_mul_f32 v[4:5], v[4:5], v[12:13]
	v_pk_mul_f32 v[6:7], v[6:7], v[14:15]
	v_pk_mul_f32 v[2:3], v[4:5], v[2:3]
	v_pk_mul_f32 v[4:5], v[6:7], v[8:9]
	v_cvt_pk_bf16_f32 v2, v2, v3
	v_cvt_pk_bf16_f32 v3, v4, v5
	global_store_dwordx2 v[16:17], v[2:3], off offset:32
	s_waitcnt vmcnt(0)

; template <int N> DI void wait_vm() { asm volatile("s_waitcnt vmcnt(%0)" ::"n"(N) : "memory"); }
; DI void raw_barrier() { asm volatile("" ::: "memory"); __builtin_amdgcn_s_barrier(); asm volatile("" ::: "memory"); }
;     ...
;     __syncthreads();
; #pragma unroll
;     for (int d = 0; d < D; ++d) issue(d, d);
;     int cb = 0, ib = D;
;     for (int kt = 0; kt < KT; ++kt) {
;         if (D > 1 && kt + D - 1 < KT) wait_vm<(D - 1) * NIT>(); else wait_vm<0>();
;         raw_barrier();
;         compute(cb, kt + D < KT, kt + D, ib);
;         cb = (cb + 1 == NST) ? 0 : cb + 1;
;         ib = (ib + 1 == NST) ? 0 : ib + 1;
;     }
.Lpo1_c_entry:
	v_subrev_u32_e32 v246, 0x100, v212
	v_readfirstlane_b32 s96, v130
	v_readfirstlane_b32 s97, v131
	v_readfirstlane_b32 s94, v0
	s_nop 3
	s_sub_u32 s96, s96, s94
	s_subb_u32 s97, s97, 0
	s_add_i32 s94, s33, 2
	v_lshrrev_b32_e32 v247, 5, v246
	v_add_u32_e32 v247, s94, v247
	v_and_b32_e32 v247, 31, v247
	v_and_b32_e32 v199, 31, v246
	v_lshlrev_b32_e32 v199, 7, v199
	v_lshl_or_b32 v247, v247, 12, v199
	s_nop 1
	global_load_dword v247, v247, s[96:97]
	v_readlane_b32 s91, v244, 36
	v_readfirstlane_b32 s95, v246
	s_nop 3
	s_lshr_b32 s91, s91, 3
	s_lshr_b32 s95, s95, 6
	s_mov_b32 s9, 2
	s_waitcnt vmcnt(1)
	s_barrier
	v_add_u32_e32 v197, v140, v141
	v_add_u32_e32 v196, v140, v139
	ds_read_b128 v[146:149], v196
	ds_read_b128 v[154:157], v196 offset:1024
	ds_read_b128 v[182:185], v196 offset:2048
	ds_read_b128 v[142:145], v197 offset:4096
	ds_read_b128 v[150:153], v197 offset:5120
	ds_read_b128 v[158:161], v197 offset:6144
	ds_read_b128 v[162:165], v197 offset:7168
	ds_read_b128 v[166:169], v197 offset:8192
	ds_read_b128 v[170:173], v197 offset:9216
	ds_read_b128 v[174:177], v197 offset:10240
	ds_read_b128 v[178:181], v197 offset:11264
	ds_read_b128 v[186:189], v196 offset:3072

; template <int N> DI void wait_vm() { asm volatile("s_waitcnt vmcnt(%0)" ::"n"(N) : "memory"); }
; DI void raw_barrier() { asm volatile("" ::: "memory"); __builtin_amdgcn_s_barrier(); asm volatile("" ::: "memory"); }
;     ...
;     for (int kt = 0; kt < KT; ++kt) {
;         if (D > 1 && kt + D - 1 < KT) wait_vm<(D - 1) * NIT>(); else wait_vm<0>();
;         raw_barrier();
;         compute(cb, kt + D < KT, kt + D, ib);
;         cb = (cb + 1 == NST) ? 0 : cb + 1;
;         ib = (ib + 1 == NST) ? 0 : ib + 1;
;     }
.Lpo1_ypf_skip:
	s_and_b32 s94, s9, 3
	s_cmp_lg_u32 s94, 2
	s_cbranch_scc1 .Lpo1_wpf_skip
	s_cmp_lg_u32 s95, 0
	s_cbranch_scc1 .Lpo1_wpf_skip
	s_lshr_b32 s94, s91, 3
	s_add_i32 s94, s94, s9
	s_add_i32 s94, s94, s33
	s_add_i32 s94, s94, 4
	s_and_b32 s94, s94, 31
	s_lshl_b32 s94, s94, 16
	s_and_b32 s92, s91, 7
	s_lshl_b32 s92, s92, 13
	s_add_u32 s94, s94, s92
	s_add_u32 s92, s70, s94
	s_addc_u32 s93, s71, 0
	v_lshlrev_b32_e32 v199, 7, v246
	global_load_dword v247, v199, s[92:93]

; template <int N> DI void wait_vm() { asm volatile("s_waitcnt vmcnt(%0)" ::"n"(N) : "memory"); }
; DI void raw_barrier() { asm volatile("" ::: "memory"); __builtin_amdgcn_s_barrier(); asm volatile("" ::: "memory"); }
;     ...
;     for (int kt = 0; kt < KT; ++kt) {
;         if (D > 1 && kt + D - 1 < KT) wait_vm<(D - 1) * NIT>(); else wait_vm<0>();
;         raw_barrier();
;         compute(cb, kt + D < KT, kt + D, ib);
;         cb = (cb + 1 == NST) ? 0 : cb + 1;
;         ib = (ib + 1 == NST) ? 0 : ib + 1;
;     }
;     __syncthreads();
; DI void unit_O(const Params& p, char* lds, int l, int tile, int glu_tiles, int tile_b) {
;     ...
;     const int xrot = (int)(((blockIdx.x >> 3) + (blockIdx.x & 7) * 4) & 31) * 4;
;     const bf16_t* xbres = WS_PTR(const bf16_t, OFF_XB1) + ((size_t)((tile >> 1) * 32) * 128 + (tile & 1) * 64) * 32;
;     auto issue_x = [&](int half) {
;         if (l == 0) {
; #pragma unroll 1
;             for (int i = 0; i < 16; ++i) {
;                 const int pc = (wid * 16 + i + xrot) & 127, row = pc >> 2, phys = (pc & 3) * 64 + lane, logical = phys ^ (row & 15);
;                 __builtin_amdgcn_global_load_lds((const unsigned*)(xres + (r0 + half * 32 + row) * 1024 + logical * 4), (unsigned*)(XR + pc * 1024 + lane * 16), 16, 0, 0);
;             }
;         } else {
; #pragma unroll 1
;             for (int i = 0; i < 8; ++i) {
;                 const int pc = (wid * 8 + i + (xrot >> 1)) & 63, kt = pc >> 1, sub = pc & 1;
;                 __builtin_amdgcn_global_load_lds((const unsigned*)(xbres + ((size_t)kt * 128 + half * 32) * 32 + sub * 512 + lane * 8), (unsigned*)(XR + pc * 1024 + lane * 16), 16, 0, 0);
;             }
;         }
;     };
;     issue_x(0);
;     {
;         const float* gsrc = (tid < 256) ? (p.ln_g + l * 1024 + tid * 4) : (p.ln_b + l * 1024 + (tid - 256) * 4);
;         *(f32x4*)(GB + tid * 4) = *(const f32x4*)gsrc;
;     }
.Lpo1_join:
.LBB0_100:
	s_waitcnt vmcnt(0)
	v_add_u32_e32 v0, 0x11000, v140
	s_barrier
	v_add_u32_e32 v134, v0, v141
	v_add_u32_e32 v0, v0, v139
	ds_read_b128 v[130:133], v134 offset:4096
	ds_read_b128 v[138:141], v0
	ds_read_b128 v[142:145], v134 offset:5120
	ds_read_b128 v[146:149], v0 offset:1024
	ds_read_b128 v[150:153], v134 offset:6144
	ds_read_b128 v[154:157], v134 offset:7168
	ds_read_b128 v[158:161], v134 offset:8192
	ds_read_b128 v[162:165], v134 offset:9216
	ds_read_b128 v[166:169], v134 offset:10240
	ds_read_b128 v[170:173], v134 offset:11264
	ds_read_b128 v[174:177], v0 offset:2048
	ds_read_b128 v[178:181], v0 offset:3072
	s_waitcnt lgkmcnt(0)
	v_mfma_f32_16x16x32_bf16 v[98:101], v[130:133], v[138:141], v[98:101]
	v_and_b32_e32 v197, 63, v136
	v_ashrrev_i32_e32 v236, 6, v136
	v_mfma_f32_16x16x32_bf16 v[94:97], v[142:145], v[138:141], v[94:97]
	v_mfma_f32_16x16x32_bf16 v[90:93], v[150:153], v[138:141], v[90:93]
	v_mfma_f32_16x16x32_bf16 v[86:89], v[154:157], v[138:141], v[86:89]
	v_mfma_f32_16x16x32_bf16 v[82:85], v[158:161], v[138:141], v[82:85]
	v_mfma_f32_16x16x32_bf16 v[78:81], v[162:165], v[138:141], v[78:81]
	v_mfma_f32_16x16x32_bf16 v[74:77], v[166:169], v[138:141], v[74:77]
	v_mfma_f32_16x16x32_bf16 v[70:73], v[170:173], v[138:141], v[70:73]
	v_mfma_f32_16x16x32_bf16 v[126:129], v[130:133], v[146:149], v[126:129]
	v_mfma_f32_16x16x32_bf16 v[122:125], v[142:145], v[146:149], v[122:125]
	v_mfma_f32_16x16x32_bf16 v[118:121], v[150:153], v[146:149], v[118:121]
	v_mfma_f32_16x16x32_bf16 v[114:117], v[154:157], v[146:149], v[114:117]
	v_mfma_f32_16x16x32_bf16 v[110:113], v[158:161], v[146:149], v[110:113]
	v_mfma_f32_16x16x32_bf16 v[106:109], v[162:165], v[146:149], v[106:109]
	v_mfma_f32_16x16x32_bf16 v[102:105], v[166:169], v[146:149], v[102:105]
	v_mfma_f32_16x16x32_bf16 v[66:69], v[170:173], v[146:149], v[66:69]
	v_mfma_f32_16x16x32_bf16 v[34:37], v[130:133], v[174:177], v[34:37]
	v_mfma_f32_16x16x32_bf16 v[30:33], v[142:145], v[174:177], v[30:33]
	v_mfma_f32_16x16x32_bf16 v[26:29], v[150:153], v[174:177], v[26:29]
	v_mfma_f32_16x16x32_bf16 v[22:25], v[154:157], v[174:177], v[22:25]
	v_mfma_f32_16x16x32_bf16 v[18:21], v[158:161], v[174:177], v[18:21]
	v_mfma_f32_16x16x32_bf16 v[14:17], v[162:165], v[174:177], v[14:17]
	v_mfma_f32_16x16x32_bf16 v[10:13], v[166:169], v[174:177], v[10:13]
	v_mfma_f32_16x16x32_bf16 v[6:9], v[170:173], v[174:177], v[6:9]
	v_mfma_f32_16x16x32_bf16 v[62:65], v[130:133], v[178:181], v[62:65]
	v_mfma_f32_16x16x32_bf16 v[58:61], v[142:145], v[178:181], v[58:61]
	v_mfma_f32_16x16x32_bf16 v[54:57], v[150:153], v[178:181], v[54:57]
	v_mfma_f32_16x16x32_bf16 v[50:53], v[154:157], v[178:181], v[50:53]
	v_mfma_f32_16x16x32_bf16 v[46:49], v[158:161], v[178:181], v[46:49]
	v_mfma_f32_16x16x32_bf16 v[42:45], v[162:165], v[178:181], v[42:45]
	v_mfma_f32_16x16x32_bf16 v[38:41], v[166:169], v[178:181], v[38:41]
	v_mfma_f32_16x16x32_bf16 v[2:5], v[170:173], v[178:181], v[2:5]
	s_barrier
	s_not_b64 s[6:7], s[10:11]
	v_lshrrev_b32_e32 v199, 5, v212
	v_add_u32_e32 v199, s33, v199
	v_and_b32_e32 v199, 31, v199
	v_and_b32_e32 v198, 31, v212
	v_lshlrev_b32_e32 v198, 7, v198
	v_lshl_or_b32 v199, v199, 12, v198
	s_lshl_b32 s94, s48, 17
	s_add_u32 s94, s54, s94
	s_addc_u32 s95, s55, 0
	global_load_dword v199, v199, s[94:95]
	v_and_b32_e32 v138, 15, v212
	v_bfe_u32 v139, v212, 4, 2
	v_lshrrev_b32_e32 v140, 6, v212
	v_and_b32_e32 v141, 63, v212
	v_readfirstlane_b32 s90, v140
	v_and_b32_e32 v142, 0xff, v212
	v_lshlrev_b32_e32 v142, 4, v142
	s_cmp_lt_u32 s90, 4
	s_cselect_b32 s92, s14, s12
	s_cselect_b32 s93, s15, s13
	s_nop 3
	global_load_dwordx4 v[176:179], v142, s[92:93]
	v_lshlrev_b32_e32 v143, 4, v212
	v_add_u32_e32 v143, 0x20000, v143
	v_lshlrev_b32_e32 v134, 6, v138
	v_add_u32_e32 v135, 0x22000, v134
	v_lshl_add_u32 v134, v140, 3, v135
	v_lshlrev_b32_e32 v136, 9, v140
	v_lshl_add_u32 v136, v139, 4, v136
	v_add_u32_e32 v136, 0x20000, v136
	s_cmp_lg_u64 s[10:11], 0
	s_cbranch_scc1 .Le1_l1
	s_lshl_b32 s40, s34, 18
	s_lshl_b32 s91, s90, 13
	s_add_u32 s96, s52, s40
	s_addc_u32 s97, s53, 0
	s_add_u32 s96, s96, s91
	s_addc_u32 s97, s97, 0
	s_lshl_b32 s40, s90, 1
	v_xor_b32_e32 v208, s40, v141
	v_lshlrev_b32_e32 v208, 4, v208
	s_add_u32 s40, s40, 1
	v_xor_b32_e32 v209, s40, v141
	v_lshlrev_b32_e32 v209, 4, v209
	v_lshlrev_b32_e32 v133, 12, v138
	v_lshl_add_u32 v133, v140, 9, v133
	v_add_u32_e32 v200, 0, v139
	v_xor_b32_e32 v200, v200, v138
	v_lshl_add_u32 v200, v200, 4, v133
	v_add_u32_e32 v204, 0x10000, v200
	v_add_u32_e32 v201, 4, v139
	v_xor_b32_e32 v201, v201, v138
	v_lshl_add_u32 v201, v201, 4, v133
	v_add_u32_e32 v205, 0x10000, v201
	v_add_u32_e32 v202, 8, v139
	v_xor_b32_e32 v202, v202, v138
	v_lshl_add_u32 v202, v202, 4, v133
	v_add_u32_e32 v206, 0x10000, v202
	v_add_u32_e32 v203, 12, v139
	v_xor_b32_e32 v203, v203, v138
	v_lshl_add_u32 v203, v203, 4, v133
	v_add_u32_e32 v207, 0x10000, v203
	v_and_b32_e32 v137, 1, v139
	v_lshlrev_b32_e32 v137, 5, v137
	v_lshrrev_b32_e32 v130, 1, v139
	v_lshl_or_b32 v137, v130, 4, v137
	v_lshl_or_b32 v137, v138, 6, v137
	v_lshl_or_b32 v137, v140, 15, v137
	s_lshr_b32 s40, s34, 1
	s_lshl_b32 s40, s40, 18
	s_and_b32 s46, s34, 1
	s_lshl_b32 s46, s46, 12
	s_add_u32 s40, s40, s46
	s_add_u32 s78, s56, s40
	s_addc_u32 s79, s57, 0
	s_add_u32 s92, s96, 0x0
	s_addc_u32 s93, s97, 0
	s_add_u32 s40, s91, 0x0
	s_mov_b32 m0, s40
	s_nop 0
	global_load_lds_dwordx4 v208, s[92:93]
	global_load_lds_dwordx4 v208, s[92:93] offset:1024
	global_load_lds_dwordx4 v208, s[92:93] offset:2048
	global_load_lds_dwordx4 v208, s[92:93] offset:3072
	s_add_u32 s92, s96, 0x1000
	s_addc_u32 s93, s97, 0
	s_add_u32 s40, s91, 0x1000
	s_mov_b32 m0, s40
	s_nop 0
	global_load_lds_dwordx4 v209, s[92:93]
	global_load_lds_dwordx4 v209, s[92:93] offset:1024
	global_load_lds_dwordx4 v209, s[92:93] offset:2048
	global_load_lds_dwordx4 v209, s[92:93] offset:3072
	s_add_u32 s92, s96, 0x10000
	s_addc_u32 s93, s97, 0
	s_add_u32 s40, s91, 0x10000
	s_mov_b32 m0, s40
	s_nop 0
	global_load_lds_dwordx4 v208, s[92:93]
	global_load_lds_dwordx4 v208, s[92:93] offset:1024
	global_load_lds_dwordx4 v208, s[92:93] offset:2048
	global_load_lds_dwordx4 v208, s[92:93] offset:3072
	s_add_u32 s92, s96, 0x11000
	s_addc_u32 s93, s97, 0
	s_add_u32 s40, s91, 0x11000
	s_mov_b32 m0, s40
	s_nop 0
	global_load_lds_dwordx4 v209, s[92:93]
	global_load_lds_dwordx4 v209, s[92:93] offset:1024
	global_load_lds_dwordx4 v209, s[92:93] offset:2048
	global_load_lds_dwordx4 v209, s[92:93] offset:3072
	s_waitcnt vmcnt(16)
	ds_write_b128 v143, v[176:179]
	s_waitcnt vmcnt(8) lgkmcnt(0)
	s_barrier
; DI float bf2f(unsigned b) { return __uint_as_float(b << 16); }
; DI void unit_O(const Params& p, char* lds, int l, int tile, int glu_tiles, int tile_b) {
;     ...
;         float s2[2], ss2[2];
; #pragma unroll
;         for (int mh = 0; mh < 2; ++mh) {
;             const int mt = half * 2 + mh, rl = mh * 16 + l15;
;             float s = 0.f, ss = 0.f;
; #pragma unroll
;             for (int nt = 0; nt < 8; ++nt) {
;                 f32x4 xr;
;                 if (l == 0) {
;                     const int chunk = wid * 32 + nt * 4 + quad;
;                     xr = *(const f32x4*)(XR + rl * 4096 + ((chunk ^ l15) << 4));
;                 } else {
;                     const u32x2 hb = *(const u32x2*)(XR + ((wid * 4 + (nt >> 1)) * 32 + rl) * 64 + (nt & 1) * 32 + quad * 8);
;                     xr = (f32x4){bf2f(hb[0] & 0xffffu), bf2f(hb[0] >> 16), bf2f(hb[1] & 0xffffu), bf2f(hb[1] >> 16)};
;                 }
; #pragma unroll
;                 for (int i = 0; i < 4; ++i) { const float v = acc[mt][nt][i] + DN_ALPHA * xr[i]; acc[mt][nt][i] = v; s += v; ss += v * v; }
;             }
;             s2[mh] = s; ss2[mh] = ss;
;         }
; #pragma unroll
;         for (int mh = 0; mh < 2; ++mh) { s2[mh] += __shfl_xor(s2[mh], 16); ss2[mh] += __shfl_xor(ss2[mh], 16); }
; #pragma unroll
;         for (int mh = 0; mh < 2; ++mh) { s2[mh] += __shfl_xor(s2[mh], 32); ss2[mh] += __shfl_xor(ss2[mh], 32); }
;         if (quad == 0) {
; #pragma unroll
;             for (int mh = 0; mh < 2; ++mh) *(f32x2*)&red[((mh * 16 + l15) * 8 + wid) * 2] = (f32x2){s2[mh], ss2[mh]};
;         }
;         __syncthreads();
;         if (half == 0) issue_x(1);
; #pragma unroll
;         for (int mh = 0; mh < 2; ++mh) {
;             const int mt = half * 2 + mh, rl = mh * 16 + l15, row = mt * 16 + l15;
;             float s = 0.f, ss = 0.f;
; #pragma unroll
;             for (int w = 0; w < 4; ++w) { const f32x4 v = *(const f32x4*)&red[rl * 16 + 4 * w]; s += v[0] + v[2]; ss += v[1] + v[3]; }
;             const float mu = s * (1.f / 1024.f);
;             const float var = ss * (1.f / 1024.f) - mu * mu;
;             const float rs = rsqrtf(var + LN_EPS);
	ds_read_b128 v[144:147], v200
	ds_read_b128 v[148:151], v201
	ds_read_b128 v[152:155], v202
	ds_read_b128 v[156:159], v203
	ds_read_b128 v[160:163], v200 offset:256
	ds_read_b128 v[164:167], v201 offset:256
	ds_read_b128 v[168:171], v202 offset:256
	ds_read_b128 v[172:175], v203 offset:256
	s_waitcnt lgkmcnt(7)
	v_fmac_f32_e32 v98, s58, v144
	v_fmac_f32_e32 v99, s58, v145
	v_fmac_f32_e32 v100, s58, v146
	v_fmac_f32_e32 v101, s58, v147
	v_mov_b32_e32 v196, v98
	v_mul_f32_e32 v197, v98, v98
	v_mov_b32_e32 v130, v99
	v_mul_f32_e32 v142, v99, v99
	v_add_f32_e32 v196, v196, v100
	v_fmac_f32_e32 v197, v100, v100
	v_add_f32_e32 v130, v130, v101
	v_fmac_f32_e32 v142, v101, v101
	s_waitcnt lgkmcnt(6)
	v_fmac_f32_e32 v94, s58, v148
	v_fmac_f32_e32 v95, s58, v149
	v_fmac_f32_e32 v96, s58, v150
	v_fmac_f32_e32 v97, s58, v151
	v_add_f32_e32 v196, v196, v94
	v_fmac_f32_e32 v197, v94, v94
	v_add_f32_e32 v130, v130, v95
	v_fmac_f32_e32 v142, v95, v95
	v_add_f32_e32 v196, v196, v96
	v_fmac_f32_e32 v197, v96, v96
	v_add_f32_e32 v130, v130, v97
	v_fmac_f32_e32 v142, v97, v97
	s_waitcnt lgkmcnt(5)
	v_fmac_f32_e32 v90, s58, v152
	v_fmac_f32_e32 v91, s58, v153
	v_fmac_f32_e32 v92, s58, v154
	v_fmac_f32_e32 v93, s58, v155
	v_add_f32_e32 v196, v196, v90
	v_fmac_f32_e32 v197, v90, v90
	v_add_f32_e32 v130, v130, v91
	v_fmac_f32_e32 v142, v91, v91
	v_add_f32_e32 v196, v196, v92
	v_fmac_f32_e32 v197, v92, v92
	v_add_f32_e32 v130, v130, v93
	v_fmac_f32_e32 v142, v93, v93
	s_waitcnt lgkmcnt(4)
	v_fmac_f32_e32 v86, s58, v156
	v_fmac_f32_e32 v87, s58, v157
	v_fmac_f32_e32 v88, s58, v158
	v_fmac_f32_e32 v89, s58, v159
	v_add_f32_e32 v196, v196, v86
	v_fmac_f32_e32 v197, v86, v86
	v_add_f32_e32 v130, v130, v87
	v_fmac_f32_e32 v142, v87, v87
	v_add_f32_e32 v196, v196, v88
	v_fmac_f32_e32 v197, v88, v88
	v_add_f32_e32 v130, v130, v89
	v_fmac_f32_e32 v142, v89, v89
	s_waitcnt lgkmcnt(3)
	v_fmac_f32_e32 v82, s58, v160
	v_fmac_f32_e32 v83, s58, v161
	v_fmac_f32_e32 v84, s58, v162
	v_fmac_f32_e32 v85, s58, v163
	v_add_f32_e32 v196, v196, v82
	v_fmac_f32_e32 v197, v82, v82
	v_add_f32_e32 v130, v130, v83
	v_fmac_f32_e32 v142, v83, v83
	v_add_f32_e32 v196, v196, v84
	v_fmac_f32_e32 v197, v84, v84
	v_add_f32_e32 v130, v130, v85
	v_fmac_f32_e32 v142, v85, v85
	s_waitcnt lgkmcnt(2)
	v_fmac_f32_e32 v78, s58, v164
	v_fmac_f32_e32 v79, s58, v165
	v_fmac_f32_e32 v80, s58, v166
	v_fmac_f32_e32 v81, s58, v167
	v_add_f32_e32 v196, v196, v78
	v_fmac_f32_e32 v197, v78, v78
	v_add_f32_e32 v130, v130, v79
	v_fmac_f32_e32 v142, v79, v79
	v_add_f32_e32 v196, v196, v80
	v_fmac_f32_e32 v197, v80, v80
	v_add_f32_e32 v130, v130, v81
	v_fmac_f32_e32 v142, v81, v81
	s_waitcnt lgkmcnt(1)
	v_fmac_f32_e32 v74, s58, v168
	v_fmac_f32_e32 v75, s58, v169
	v_fmac_f32_e32 v76, s58, v170
	v_fmac_f32_e32 v77, s58, v171
	v_add_f32_e32 v196, v196, v74
	v_fmac_f32_e32 v197, v74, v74
	v_add_f32_e32 v130, v130, v75
	v_fmac_f32_e32 v142, v75, v75
	v_add_f32_e32 v196, v196, v76
	v_fmac_f32_e32 v197, v76, v76
	v_add_f32_e32 v130, v130, v77
	v_fmac_f32_e32 v142, v77, v77
	s_waitcnt lgkmcnt(0)
	v_fmac_f32_e32 v70, s58, v172
	v_fmac_f32_e32 v71, s58, v173
	v_fmac_f32_e32 v72, s58, v174
	v_fmac_f32_e32 v73, s58, v175
	v_add_f32_e32 v196, v196, v70
	v_fmac_f32_e32 v197, v70, v70
	v_add_f32_e32 v130, v130, v71
	v_fmac_f32_e32 v142, v71, v71
	v_add_f32_e32 v196, v196, v72
	v_fmac_f32_e32 v197, v72, v72
	v_add_f32_e32 v130, v130, v73
	v_fmac_f32_e32 v142, v73, v73
	v_add_f32_e32 v196, v196, v130
	v_add_f32_e32 v197, v197, v142
	v_mov_b32_e32 v198, v196
	v_mov_b32_e32 v199, v197
	s_nop 1
	v_permlane16_swap_b32 v198, v196
	v_permlane16_swap_b32 v199, v197
	v_add_f32_e32 v196, v196, v198
	v_add_f32_e32 v197, v197, v199
	v_mov_b32_e32 v198, v196
	v_mov_b32_e32 v199, v197
	s_nop 1
	v_permlane32_swap_b32 v198, v196
	v_permlane32_swap_b32 v199, v197
	v_add_f32_e32 v196, v196, v198
	v_add_f32_e32 v197, v197, v199
	s_mov_b64 exec, 0xffff
	ds_write_b64 v134, v[196:197]
	s_mov_b64 exec, -1
	s_waitcnt lgkmcnt(0)
	s_barrier
	s_add_u32 s92, s96, 0x20000
	s_addc_u32 s93, s97, 0
	s_add_u32 s40, s91, 0x0
	s_mov_b32 m0, s40
	s_nop 0
	global_load_lds_dwordx4 v208, s[92:93]
	global_load_lds_dwordx4 v208, s[92:93] offset:1024
	global_load_lds_dwordx4 v208, s[92:93] offset:2048
	global_load_lds_dwordx4 v208, s[92:93] offset:3072
	s_add_u32 s92, s96, 0x21000
	s_addc_u32 s93, s97, 0
	s_add_u32 s40, s91, 0x1000
	s_mov_b32 m0, s40
	s_nop 0
	global_load_lds_dwordx4 v209, s[92:93]
	global_load_lds_dwordx4 v209, s[92:93] offset:1024
	global_load_lds_dwordx4 v209, s[92:93] offset:2048
	global_load_lds_dwordx4 v209, s[92:93] offset:3072
	ds_read_b128 v[160:163], v135 offset:0
	ds_read_b128 v[164:167], v135 offset:16
	ds_read_b128 v[168:171], v135 offset:32
	ds_read_b128 v[172:175], v135 offset:48
	s_waitcnt lgkmcnt(0)
	v_add_f32_e32 v160, v160, v162
	v_add_f32_e32 v161, v161, v163
	v_add_f32_e32 v164, v164, v166
	v_add_f32_e32 v165, v165, v167
	v_add_f32_e32 v168, v168, v170
	v_add_f32_e32 v169, v169, v171
	v_add_f32_e32 v172, v172, v174
	v_add_f32_e32 v173, v173, v175
	v_add_f32_e32 v160, v160, v164
	v_add_f32_e32 v161, v161, v165
	v_add_f32_e32 v168, v168, v172
	v_add_f32_e32 v169, v169, v173
	v_add_f32_e32 v160, v160, v168
	v_add_f32_e32 v161, v161, v169
	v_mul_f32_e32 v192, 0x3a800000, v160
	v_mul_f32_e32 v193, 0x3a800000, v161
	v_fma_f32 v193, -v192, v192, v193
	v_add_f32_e32 v193, 0x3727c5ac, v193
	v_rsq_f32_e32 v193, v193
	s_nop 0
	s_add_u32 s94, s78, 0x0
	s_addc_u32 s95, s79, 0
	ds_read_b128 v[176:179], v136
	ds_read_b128 v[180:183], v136 offset:4096
	ds_read_b128 v[184:187], v136 offset:64
	ds_read_b128 v[188:191], v136 offset:4160
	s_waitcnt lgkmcnt(2)
; DI unsigned pk2(float lo, float hi) { const f32x2 v = {lo, hi}; const bf16x2_t b = __builtin_convertvector(v, bf16x2_t); return __builtin_bit_cast(unsigned, b); }
; DI size_t xb_off(int tok, int col) { return ((size_t)(((tok >> 7) * 32 + (col >> 5)) * 128 + (tok & 127))) * 32 + (col & 31); }
; DI void unit_O(const Params& p, char* lds, int l, int tile, int glu_tiles, int tile_b) {
;     ...
;             float* orow = xo + (r0 + row) * 1024 + wid * 128 + quad * 4;
;             bf16_t* brow = xbo + xb_off((int)r0 + row, wid * 128) + quad * 4;
;             const float* gp = GB + wid * 128 + quad * 4;
; #pragma unroll
;             for (int nt = 0; nt < 8; ++nt) {
;                 const f32x4 g = *(const f32x4*)(gp + nt * 16), bb = *(const f32x4*)(gp + 1024 + nt * 16);
;                 f32x4 o;
; #pragma unroll
;                 for (int i = 0; i < 4; ++i) o[i] = (acc[mt][nt][i] - mu) * rs * g[i] + bb[i];
;                 if (l == 0) *(u32x2*)(brow + (nt >> 1) * 4096 + (nt & 1) * 16) = (u32x2){pk2(o[0], o[1]), pk2(o[2], o[3])};
;                 else *(f32x4*)(orow + nt * 16) = o;
;             }
;         }
	v_sub_f32_e32 v98, v98, v192
	v_mul_f32_e32 v98, v98, v193
	v_fma_f32 v98, v176, v98, v180
	v_sub_f32_e32 v99, v99, v192
	v_mul_f32_e32 v99, v99, v193
	v_fma_f32 v99, v177, v99, v181
	v_sub_f32_e32 v100, v100, v192
	v_mul_f32_e32 v100, v100, v193
	v_fma_f32 v100, v178, v100, v182
	v_sub_f32_e32 v101, v101, v192
	v_mul_f32_e32 v101, v101, v193
	v_fma_f32 v101, v179, v101, v183
	v_cvt_pk_bf16_f32 v144, v98, v99
	v_cvt_pk_bf16_f32 v145, v100, v101
	ds_read_b128 v[176:179], v136 offset:128
	ds_read_b128 v[180:183], v136 offset:4224
	s_waitcnt lgkmcnt(2)
	v_sub_f32_e32 v94, v94, v192
	v_mul_f32_e32 v94, v94, v193
	v_fma_f32 v94, v184, v94, v188
	v_sub_f32_e32 v95, v95, v192
	v_mul_f32_e32 v95, v95, v193
	v_fma_f32 v95, v185, v95, v189
	v_sub_f32_e32 v96, v96, v192
	v_mul_f32_e32 v96, v96, v193
	v_fma_f32 v96, v186, v96, v190
	v_sub_f32_e32 v97, v97, v192
	v_mul_f32_e32 v97, v97, v193
	v_fma_f32 v97, v187, v97, v191
	v_cvt_pk_bf16_f32 v146, v94, v95
	v_cvt_pk_bf16_f32 v147, v96, v97
	s_nop 1
	v_permlane16_swap_b32 v144, v146
	v_permlane16_swap_b32 v145, v147
	global_store_dwordx4 v137, v[144:147], s[94:95]
	s_add_u32 s94, s94, 0x2000
	s_addc_u32 s95, s95, 0
	ds_read_b128 v[184:187], v136 offset:192
	ds_read_b128 v[188:191], v136 offset:4288
	s_waitcnt lgkmcnt(2)
	v_sub_f32_e32 v90, v90, v192
	v_mul_f32_e32 v90, v90, v193
	v_fma_f32 v90, v176, v90, v180
	v_sub_f32_e32 v91, v91, v192
	v_mul_f32_e32 v91, v91, v193
	v_fma_f32 v91, v177, v91, v181
	v_sub_f32_e32 v92, v92, v192
	v_mul_f32_e32 v92, v92, v193
	v_fma_f32 v92, v178, v92, v182
	v_sub_f32_e32 v93, v93, v192
	v_mul_f32_e32 v93, v93, v193
	v_fma_f32 v93, v179, v93, v183
	v_cvt_pk_bf16_f32 v152, v90, v91
	v_cvt_pk_bf16_f32 v153, v92, v93
	ds_read_b128 v[176:179], v136 offset:256
	ds_read_b128 v[180:183], v136 offset:4352
	s_waitcnt lgkmcnt(2)
	v_sub_f32_e32 v86, v86, v192
	v_mul_f32_e32 v86, v86, v193
	v_fma_f32 v86, v184, v86, v188
	v_sub_f32_e32 v87, v87, v192
	v_mul_f32_e32 v87, v87, v193
	v_fma_f32 v87, v185, v87, v189
	v_sub_f32_e32 v88, v88, v192
	v_mul_f32_e32 v88, v88, v193
	v_fma_f32 v88, v186, v88, v190
	v_sub_f32_e32 v89, v89, v192
	v_mul_f32_e32 v89, v89, v193
	v_fma_f32 v89, v187, v89, v191
	v_cvt_pk_bf16_f32 v154, v86, v87
	v_cvt_pk_bf16_f32 v155, v88, v89
	s_nop 1
	v_permlane16_swap_b32 v152, v154
	v_permlane16_swap_b32 v153, v155
	global_store_dwordx4 v137, v[152:155], s[94:95]
	s_add_u32 s94, s94, 0x2000
	s_addc_u32 s95, s95, 0
	ds_read_b128 v[184:187], v136 offset:320
	ds_read_b128 v[188:191], v136 offset:4416
	s_waitcnt lgkmcnt(2)
	v_sub_f32_e32 v82, v82, v192
	v_mul_f32_e32 v82, v82, v193
	v_fma_f32 v82, v176, v82, v180
	v_sub_f32_e32 v83, v83, v192
	v_mul_f32_e32 v83, v83, v193
	v_fma_f32 v83, v177, v83, v181
	v_sub_f32_e32 v84, v84, v192
	v_mul_f32_e32 v84, v84, v193
	v_fma_f32 v84, v178, v84, v182
	v_sub_f32_e32 v85, v85, v192
	v_mul_f32_e32 v85, v85, v193
	v_fma_f32 v85, v179, v85, v183
	v_cvt_pk_bf16_f32 v144, v82, v83
	v_cvt_pk_bf16_f32 v145, v84, v85
	ds_read_b128 v[176:179], v136 offset:384
	ds_read_b128 v[180:183], v136 offset:4480
	s_waitcnt lgkmcnt(2)
	v_sub_f32_e32 v78, v78, v192
	v_mul_f32_e32 v78, v78, v193
	v_fma_f32 v78, v184, v78, v188
	v_sub_f32_e32 v79, v79, v192
	v_mul_f32_e32 v79, v79, v193
	v_fma_f32 v79, v185, v79, v189
	v_sub_f32_e32 v80, v80, v192
	v_mul_f32_e32 v80, v80, v193
	v_fma_f32 v80, v186, v80, v190
	v_sub_f32_e32 v81, v81, v192
	v_mul_f32_e32 v81, v81, v193
	v_fma_f32 v81, v187, v81, v191
	v_cvt_pk_bf16_f32 v146, v78, v79
	v_cvt_pk_bf16_f32 v147, v80, v81
	s_nop 1
	v_permlane16_swap_b32 v144, v146
	v_permlane16_swap_b32 v145, v147
	global_store_dwordx4 v137, v[144:147], s[94:95]
	s_add_u32 s94, s94, 0x2000
	s_addc_u32 s95, s95, 0
	ds_read_b128 v[184:187], v136 offset:448
	ds_read_b128 v[188:191], v136 offset:4544
	s_waitcnt lgkmcnt(2)
	v_sub_f32_e32 v74, v74, v192
	v_mul_f32_e32 v74, v74, v193
	v_fma_f32 v74, v176, v74, v180
	v_sub_f32_e32 v75, v75, v192
	v_mul_f32_e32 v75, v75, v193
	v_fma_f32 v75, v177, v75, v181
	v_sub_f32_e32 v76, v76, v192
	v_mul_f32_e32 v76, v76, v193
	v_fma_f32 v76, v178, v76, v182
	v_sub_f32_e32 v77, v77, v192
	v_mul_f32_e32 v77, v77, v193
	v_fma_f32 v77, v179, v77, v183
	v_cvt_pk_bf16_f32 v152, v74, v75
	v_cvt_pk_bf16_f32 v153, v76, v77
	s_waitcnt lgkmcnt(0)
	v_sub_f32_e32 v70, v70, v192
	v_mul_f32_e32 v70, v70, v193
	v_fma_f32 v70, v184, v70, v188
	v_sub_f32_e32 v71, v71, v192
	v_mul_f32_e32 v71, v71, v193
	v_fma_f32 v71, v185, v71, v189
	v_sub_f32_e32 v72, v72, v192
	v_mul_f32_e32 v72, v72, v193
	v_fma_f32 v72, v186, v72, v190
	v_sub_f32_e32 v73, v73, v192
	v_mul_f32_e32 v73, v73, v193
	v_fma_f32 v73, v187, v73, v191
	v_cvt_pk_bf16_f32 v154, v70, v71
	v_cvt_pk_bf16_f32 v155, v72, v73
	s_nop 1
	v_permlane16_swap_b32 v152, v154
	v_permlane16_swap_b32 v153, v155
	global_store_dwordx4 v137, v[152:155], s[94:95]
	s_waitcnt vmcnt(12) lgkmcnt(0)
	s_barrier
; DI float bf2f(unsigned b) { return __uint_as_float(b << 16); }
; DI void unit_O(const Params& p, char* lds, int l, int tile, int glu_tiles, int tile_b) {
;     ...
;         float s2[2], ss2[2];
; #pragma unroll
;         for (int mh = 0; mh < 2; ++mh) {
;             const int mt = half * 2 + mh, rl = mh * 16 + l15;
;             float s = 0.f, ss = 0.f;
; #pragma unroll
;             for (int nt = 0; nt < 8; ++nt) {
;                 f32x4 xr;
;                 if (l == 0) {
;                     const int chunk = wid * 32 + nt * 4 + quad;
;                     xr = *(const f32x4*)(XR + rl * 4096 + ((chunk ^ l15) << 4));
;                 } else {
;                     const u32x2 hb = *(const u32x2*)(XR + ((wid * 4 + (nt >> 1)) * 32 + rl) * 64 + (nt & 1) * 32 + quad * 8);
;                     xr = (f32x4){bf2f(hb[0] & 0xffffu), bf2f(hb[0] >> 16), bf2f(hb[1] & 0xffffu), bf2f(hb[1] >> 16)};
;                 }
; #pragma unroll
;                 for (int i = 0; i < 4; ++i) { const float v = acc[mt][nt][i] + DN_ALPHA * xr[i]; acc[mt][nt][i] = v; s += v; ss += v * v; }
;             }
;             s2[mh] = s; ss2[mh] = ss;
;         }
; #pragma unroll
;         for (int mh = 0; mh < 2; ++mh) { s2[mh] += __shfl_xor(s2[mh], 16); ss2[mh] += __shfl_xor(ss2[mh], 16); }
; #pragma unroll
;         for (int mh = 0; mh < 2; ++mh) { s2[mh] += __shfl_xor(s2[mh], 32); ss2[mh] += __shfl_xor(ss2[mh], 32); }
;         if (quad == 0) {
; #pragma unroll
;             for (int mh = 0; mh < 2; ++mh) *(f32x2*)&red[((mh * 16 + l15) * 8 + wid) * 2] = (f32x2){s2[mh], ss2[mh]};
;         }
;         __syncthreads();
;         if (half == 0) issue_x(1);
; #pragma unroll
;         for (int mh = 0; mh < 2; ++mh) {
;             const int mt = half * 2 + mh, rl = mh * 16 + l15, row = mt * 16 + l15;
;             float s = 0.f, ss = 0.f;
; #pragma unroll
;             for (int w = 0; w < 4; ++w) { const f32x4 v = *(const f32x4*)&red[rl * 16 + 4 * w]; s += v[0] + v[2]; ss += v[1] + v[3]; }
;             const float mu = s * (1.f / 1024.f);
;             const float var = ss * (1.f / 1024.f) - mu * mu;
;             const float rs = rsqrtf(var + LN_EPS);
	ds_read_b128 v[144:147], v204
	ds_read_b128 v[148:151], v205
	ds_read_b128 v[152:155], v206
	ds_read_b128 v[156:159], v207
	ds_read_b128 v[160:163], v204 offset:256
	ds_read_b128 v[164:167], v205 offset:256
	ds_read_b128 v[168:171], v206 offset:256
	ds_read_b128 v[172:175], v207 offset:256
	s_waitcnt lgkmcnt(7)
	v_fmac_f32_e32 v126, s58, v144
	v_fmac_f32_e32 v127, s58, v145
	v_fmac_f32_e32 v128, s58, v146
	v_fmac_f32_e32 v129, s58, v147
	v_mov_b32_e32 v196, v126
	v_mul_f32_e32 v197, v126, v126
	v_mov_b32_e32 v130, v127
	v_mul_f32_e32 v142, v127, v127
	v_add_f32_e32 v196, v196, v128
	v_fmac_f32_e32 v197, v128, v128
	v_add_f32_e32 v130, v130, v129
	v_fmac_f32_e32 v142, v129, v129
	s_waitcnt lgkmcnt(6)
	v_fmac_f32_e32 v122, s58, v148
	v_fmac_f32_e32 v123, s58, v149
	v_fmac_f32_e32 v124, s58, v150
	v_fmac_f32_e32 v125, s58, v151
	v_add_f32_e32 v196, v196, v122
	v_fmac_f32_e32 v197, v122, v122
	v_add_f32_e32 v130, v130, v123
	v_fmac_f32_e32 v142, v123, v123
	v_add_f32_e32 v196, v196, v124
	v_fmac_f32_e32 v197, v124, v124
	v_add_f32_e32 v130, v130, v125
	v_fmac_f32_e32 v142, v125, v125
	s_waitcnt lgkmcnt(5)
	v_fmac_f32_e32 v118, s58, v152
	v_fmac_f32_e32 v119, s58, v153
	v_fmac_f32_e32 v120, s58, v154
	v_fmac_f32_e32 v121, s58, v155
	v_add_f32_e32 v196, v196, v118
	v_fmac_f32_e32 v197, v118, v118
	v_add_f32_e32 v130, v130, v119
	v_fmac_f32_e32 v142, v119, v119
	v_add_f32_e32 v196, v196, v120
	v_fmac_f32_e32 v197, v120, v120
	v_add_f32_e32 v130, v130, v121
	v_fmac_f32_e32 v142, v121, v121
	s_waitcnt lgkmcnt(4)
	v_fmac_f32_e32 v114, s58, v156
	v_fmac_f32_e32 v115, s58, v157
	v_fmac_f32_e32 v116, s58, v158
	v_fmac_f32_e32 v117, s58, v159
	v_add_f32_e32 v196, v196, v114
	v_fmac_f32_e32 v197, v114, v114
	v_add_f32_e32 v130, v130, v115
	v_fmac_f32_e32 v142, v115, v115
	v_add_f32_e32 v196, v196, v116
	v_fmac_f32_e32 v197, v116, v116
	v_add_f32_e32 v130, v130, v117
	v_fmac_f32_e32 v142, v117, v117
	s_waitcnt lgkmcnt(3)
	v_fmac_f32_e32 v110, s58, v160
	v_fmac_f32_e32 v111, s58, v161
	v_fmac_f32_e32 v112, s58, v162
	v_fmac_f32_e32 v113, s58, v163
	v_add_f32_e32 v196, v196, v110
	v_fmac_f32_e32 v197, v110, v110
	v_add_f32_e32 v130, v130, v111
	v_fmac_f32_e32 v142, v111, v111
	v_add_f32_e32 v196, v196, v112
	v_fmac_f32_e32 v197, v112, v112
	v_add_f32_e32 v130, v130, v113
	v_fmac_f32_e32 v142, v113, v113
	s_waitcnt lgkmcnt(2)
	v_fmac_f32_e32 v106, s58, v164
	v_fmac_f32_e32 v107, s58, v165
	v_fmac_f32_e32 v108, s58, v166
	v_fmac_f32_e32 v109, s58, v167
	v_add_f32_e32 v196, v196, v106
	v_fmac_f32_e32 v197, v106, v106
	v_add_f32_e32 v130, v130, v107
	v_fmac_f32_e32 v142, v107, v107
	v_add_f32_e32 v196, v196, v108
	v_fmac_f32_e32 v197, v108, v108
	v_add_f32_e32 v130, v130, v109
	v_fmac_f32_e32 v142, v109, v109
	s_waitcnt lgkmcnt(1)
	v_fmac_f32_e32 v102, s58, v168
	v_fmac_f32_e32 v103, s58, v169
	v_fmac_f32_e32 v104, s58, v170
	v_fmac_f32_e32 v105, s58, v171
	v_add_f32_e32 v196, v196, v102
	v_fmac_f32_e32 v197, v102, v102
	v_add_f32_e32 v130, v130, v103
	v_fmac_f32_e32 v142, v103, v103
	v_add_f32_e32 v196, v196, v104
	v_fmac_f32_e32 v197, v104, v104
	v_add_f32_e32 v130, v130, v105
	v_fmac_f32_e32 v142, v105, v105
	s_waitcnt lgkmcnt(0)
	v_fmac_f32_e32 v66, s58, v172
	v_fmac_f32_e32 v67, s58, v173
	v_fmac_f32_e32 v68, s58, v174
	v_fmac_f32_e32 v69, s58, v175
	v_add_f32_e32 v196, v196, v66
	v_fmac_f32_e32 v197, v66, v66
	v_add_f32_e32 v130, v130, v67
	v_fmac_f32_e32 v142, v67, v67
	v_add_f32_e32 v196, v196, v68
	v_fmac_f32_e32 v197, v68, v68
	v_add_f32_e32 v130, v130, v69
	v_fmac_f32_e32 v142, v69, v69
	v_add_f32_e32 v196, v196, v130
	v_add_f32_e32 v197, v197, v142
	v_mov_b32_e32 v198, v196
	v_mov_b32_e32 v199, v197
	s_nop 1
	v_permlane16_swap_b32 v198, v196
	v_permlane16_swap_b32 v199, v197
	v_add_f32_e32 v196, v196, v198
	v_add_f32_e32 v197, v197, v199
	v_mov_b32_e32 v198, v196
	v_mov_b32_e32 v199, v197
	s_nop 1
	v_permlane32_swap_b32 v198, v196
	v_permlane32_swap_b32 v199, v197
	v_add_f32_e32 v196, v196, v198
	v_add_f32_e32 v197, v197, v199
	s_mov_b64 exec, 0xffff
	ds_write_b64 v134, v[196:197]
	s_mov_b64 exec, -1
	s_waitcnt lgkmcnt(0)
	s_barrier
	s_add_u32 s92, s96, 0x30000
	s_addc_u32 s93, s97, 0
	s_add_u32 s40, s91, 0x10000
	s_mov_b32 m0, s40
	s_nop 0
	global_load_lds_dwordx4 v208, s[92:93]
	global_load_lds_dwordx4 v208, s[92:93] offset:1024
	global_load_lds_dwordx4 v208, s[92:93] offset:2048
	global_load_lds_dwordx4 v208, s[92:93] offset:3072
	s_add_u32 s92, s96, 0x31000
	s_addc_u32 s93, s97, 0
	s_add_u32 s40, s91, 0x11000
	s_mov_b32 m0, s40
	s_nop 0
	global_load_lds_dwordx4 v209, s[92:93]
	global_load_lds_dwordx4 v209, s[92:93] offset:1024
	global_load_lds_dwordx4 v209, s[92:93] offset:2048
	global_load_lds_dwordx4 v209, s[92:93] offset:3072
	ds_read_b128 v[160:163], v135 offset:0
	ds_read_b128 v[164:167], v135 offset:16
	ds_read_b128 v[168:171], v135 offset:32
	ds_read_b128 v[172:175], v135 offset:48
	s_waitcnt lgkmcnt(0)
	v_add_f32_e32 v160, v160, v162
	v_add_f32_e32 v161, v161, v163
	v_add_f32_e32 v164, v164, v166
	v_add_f32_e32 v165, v165, v167
	v_add_f32_e32 v168, v168, v170
	v_add_f32_e32 v169, v169, v171
	v_add_f32_e32 v172, v172, v174
	v_add_f32_e32 v173, v173, v175
	v_add_f32_e32 v160, v160, v164
	v_add_f32_e32 v161, v161, v165
	v_add_f32_e32 v168, v168, v172
	v_add_f32_e32 v169, v169, v173
	v_add_f32_e32 v160, v160, v168
	v_add_f32_e32 v161, v161, v169
	v_mul_f32_e32 v192, 0x3a800000, v160
	v_mul_f32_e32 v193, 0x3a800000, v161
	v_fma_f32 v193, -v192, v192, v193
	v_add_f32_e32 v193, 0x3727c5ac, v193
	v_rsq_f32_e32 v193, v193
	s_nop 0
	s_add_u32 s94, s78, 0x400
	s_addc_u32 s95, s79, 0
	ds_read_b128 v[176:179], v136
	ds_read_b128 v[180:183], v136 offset:4096
	ds_read_b128 v[184:187], v136 offset:64
	ds_read_b128 v[188:191], v136 offset:4160
	s_waitcnt lgkmcnt(2)
; DI unsigned pk2(float lo, float hi) { const f32x2 v = {lo, hi}; const bf16x2_t b = __builtin_convertvector(v, bf16x2_t); return __builtin_bit_cast(unsigned, b); }
; DI size_t xb_off(int tok, int col) { return ((size_t)(((tok >> 7) * 32 + (col >> 5)) * 128 + (tok & 127))) * 32 + (col & 31); }
; DI void unit_O(const Params& p, char* lds, int l, int tile, int glu_tiles, int tile_b) {
;     ...
;             float* orow = xo + (r0 + row) * 1024 + wid * 128 + quad * 4;
;             bf16_t* brow = xbo + xb_off((int)r0 + row, wid * 128) + quad * 4;
;             const float* gp = GB + wid * 128 + quad * 4;
; #pragma unroll
;             for (int nt = 0; nt < 8; ++nt) {
;                 const f32x4 g = *(const f32x4*)(gp + nt * 16), bb = *(const f32x4*)(gp + 1024 + nt * 16);
;                 f32x4 o;
; #pragma unroll
;                 for (int i = 0; i < 4; ++i) o[i] = (acc[mt][nt][i] - mu) * rs * g[i] + bb[i];
;                 if (l == 0) *(u32x2*)(brow + (nt >> 1) * 4096 + (nt & 1) * 16) = (u32x2){pk2(o[0], o[1]), pk2(o[2], o[3])};
;                 else *(f32x4*)(orow + nt * 16) = o;
;             }
;         }
	v_sub_f32_e32 v126, v126, v192
	v_mul_f32_e32 v126, v126, v193
	v_fma_f32 v126, v176, v126, v180
	v_sub_f32_e32 v127, v127, v192
	v_mul_f32_e32 v127, v127, v193
	v_fma_f32 v127, v177, v127, v181
	v_sub_f32_e32 v128, v128, v192
	v_mul_f32_e32 v128, v128, v193
	v_fma_f32 v128, v178, v128, v182
	v_sub_f32_e32 v129, v129, v192
	v_mul_f32_e32 v129, v129, v193
	v_fma_f32 v129, v179, v129, v183
	v_cvt_pk_bf16_f32 v144, v126, v127
	v_cvt_pk_bf16_f32 v145, v128, v129
	ds_read_b128 v[176:179], v136 offset:128
	ds_read_b128 v[180:183], v136 offset:4224
	s_waitcnt lgkmcnt(2)
	v_sub_f32_e32 v122, v122, v192
	v_mul_f32_e32 v122, v122, v193
	v_fma_f32 v122, v184, v122, v188
	v_sub_f32_e32 v123, v123, v192
	v_mul_f32_e32 v123, v123, v193
	v_fma_f32 v123, v185, v123, v189
	v_sub_f32_e32 v124, v124, v192
	v_mul_f32_e32 v124, v124, v193
	v_fma_f32 v124, v186, v124, v190
	v_sub_f32_e32 v125, v125, v192
	v_mul_f32_e32 v125, v125, v193
	v_fma_f32 v125, v187, v125, v191
	v_cvt_pk_bf16_f32 v146, v122, v123
	v_cvt_pk_bf16_f32 v147, v124, v125
	s_nop 1
	v_permlane16_swap_b32 v144, v146
	v_permlane16_swap_b32 v145, v147
	global_store_dwordx4 v137, v[144:147], s[94:95]
	s_add_u32 s94, s94, 0x2000
	s_addc_u32 s95, s95, 0
	ds_read_b128 v[184:187], v136 offset:192
	ds_read_b128 v[188:191], v136 offset:4288
	s_waitcnt lgkmcnt(2)
	v_sub_f32_e32 v118, v118, v192
	v_mul_f32_e32 v118, v118, v193
	v_fma_f32 v118, v176, v118, v180
	v_sub_f32_e32 v119, v119, v192
	v_mul_f32_e32 v119, v119, v193
	v_fma_f32 v119, v177, v119, v181
	v_sub_f32_e32 v120, v120, v192
	v_mul_f32_e32 v120, v120, v193
	v_fma_f32 v120, v178, v120, v182
	v_sub_f32_e32 v121, v121, v192
	v_mul_f32_e32 v121, v121, v193
	v_fma_f32 v121, v179, v121, v183
	v_cvt_pk_bf16_f32 v152, v118, v119
	v_cvt_pk_bf16_f32 v153, v120, v121
	ds_read_b128 v[176:179], v136 offset:256
	ds_read_b128 v[180:183], v136 offset:4352
	s_waitcnt lgkmcnt(2)
	v_sub_f32_e32 v114, v114, v192
	v_mul_f32_e32 v114, v114, v193
	v_fma_f32 v114, v184, v114, v188
	v_sub_f32_e32 v115, v115, v192
	v_mul_f32_e32 v115, v115, v193
	v_fma_f32 v115, v185, v115, v189
	v_sub_f32_e32 v116, v116, v192
	v_mul_f32_e32 v116, v116, v193
	v_fma_f32 v116, v186, v116, v190
	v_sub_f32_e32 v117, v117, v192
	v_mul_f32_e32 v117, v117, v193
	v_fma_f32 v117, v187, v117, v191
	v_cvt_pk_bf16_f32 v154, v114, v115
	v_cvt_pk_bf16_f32 v155, v116, v117
	s_nop 1
	v_permlane16_swap_b32 v152, v154
	v_permlane16_swap_b32 v153, v155
	global_store_dwordx4 v137, v[152:155], s[94:95]
	s_add_u32 s94, s94, 0x2000
	s_addc_u32 s95, s95, 0
	ds_read_b128 v[184:187], v136 offset:320
	ds_read_b128 v[188:191], v136 offset:4416
	s_waitcnt lgkmcnt(2)
	v_sub_f32_e32 v110, v110, v192
	v_mul_f32_e32 v110, v110, v193
	v_fma_f32 v110, v176, v110, v180
	v_sub_f32_e32 v111, v111, v192
	v_mul_f32_e32 v111, v111, v193
	v_fma_f32 v111, v177, v111, v181
	v_sub_f32_e32 v112, v112, v192
	v_mul_f32_e32 v112, v112, v193
	v_fma_f32 v112, v178, v112, v182
	v_sub_f32_e32 v113, v113, v192
	v_mul_f32_e32 v113, v113, v193
	v_fma_f32 v113, v179, v113, v183
	v_cvt_pk_bf16_f32 v144, v110, v111
	v_cvt_pk_bf16_f32 v145, v112, v113
	ds_read_b128 v[176:179], v136 offset:384
	ds_read_b128 v[180:183], v136 offset:4480
	s_waitcnt lgkmcnt(2)
	v_sub_f32_e32 v106, v106, v192
	v_mul_f32_e32 v106, v106, v193
	v_fma_f32 v106, v184, v106, v188
	v_sub_f32_e32 v107, v107, v192
	v_mul_f32_e32 v107, v107, v193
	v_fma_f32 v107, v185, v107, v189
	v_sub_f32_e32 v108, v108, v192
	v_mul_f32_e32 v108, v108, v193
	v_fma_f32 v108, v186, v108, v190
	v_sub_f32_e32 v109, v109, v192
	v_mul_f32_e32 v109, v109, v193
	v_fma_f32 v109, v187, v109, v191
	v_cvt_pk_bf16_f32 v146, v106, v107
	v_cvt_pk_bf16_f32 v147, v108, v109
	s_nop 1
	v_permlane16_swap_b32 v144, v146
	v_permlane16_swap_b32 v145, v147
	global_store_dwordx4 v137, v[144:147], s[94:95]
	s_add_u32 s94, s94, 0x2000
	s_addc_u32 s95, s95, 0
	ds_read_b128 v[184:187], v136 offset:448
	ds_read_b128 v[188:191], v136 offset:4544
	s_waitcnt lgkmcnt(2)
	v_sub_f32_e32 v102, v102, v192
	v_mul_f32_e32 v102, v102, v193
	v_fma_f32 v102, v176, v102, v180
	v_sub_f32_e32 v103, v103, v192
	v_mul_f32_e32 v103, v103, v193
	v_fma_f32 v103, v177, v103, v181
	v_sub_f32_e32 v104, v104, v192
	v_mul_f32_e32 v104, v104, v193
	v_fma_f32 v104, v178, v104, v182
	v_sub_f32_e32 v105, v105, v192
	v_mul_f32_e32 v105, v105, v193
	v_fma_f32 v105, v179, v105, v183
	v_cvt_pk_bf16_f32 v152, v102, v103
	v_cvt_pk_bf16_f32 v153, v104, v105
	s_waitcnt lgkmcnt(0)
	v_sub_f32_e32 v66, v66, v192
	v_mul_f32_e32 v66, v66, v193
	v_fma_f32 v66, v184, v66, v188
	v_sub_f32_e32 v67, v67, v192
	v_mul_f32_e32 v67, v67, v193
	v_fma_f32 v67, v185, v67, v189
	v_sub_f32_e32 v68, v68, v192
	v_mul_f32_e32 v68, v68, v193
	v_fma_f32 v68, v186, v68, v190
	v_sub_f32_e32 v69, v69, v192
	v_mul_f32_e32 v69, v69, v193
	v_fma_f32 v69, v187, v69, v191
	v_cvt_pk_bf16_f32 v154, v66, v67
	v_cvt_pk_bf16_f32 v155, v68, v69
	s_nop 1
	v_permlane16_swap_b32 v152, v154
	v_permlane16_swap_b32 v153, v155
	global_store_dwordx4 v137, v[152:155], s[94:95]
	s_waitcnt vmcnt(16) lgkmcnt(0)
	s_barrier
; DI void unit_O(const Params& p, char* lds, int l, int tile, int glu_tiles, int tile_b) {
;     ...
;         float s2[2], ss2[2];
; #pragma unroll
;         for (int mh = 0; mh < 2; ++mh) {
;             const int mt = half * 2 + mh, rl = mh * 16 + l15;
;             float s = 0.f, ss = 0.f;
; #pragma unroll
;             for (int nt = 0; nt < 8; ++nt) {
;                 f32x4 xr;
;                 if (l == 0) {
;                     const int chunk = wid * 32 + nt * 4 + quad;
;                     xr = *(const f32x4*)(XR + rl * 4096 + ((chunk ^ l15) << 4));
;                 } else {
;                     const u32x2 hb = *(const u32x2*)(XR + ((wid * 4 + (nt >> 1)) * 32 + rl) * 64 + (nt & 1) * 32 + quad * 8);
;                     xr = (f32x4){bf2f(hb[0] & 0xffffu), bf2f(hb[0] >> 16), bf2f(hb[1] & 0xffffu), bf2f(hb[1] >> 16)};
;                 }
; #pragma unroll
;                 for (int i = 0; i < 4; ++i) { const float v = acc[mt][nt][i] + DN_ALPHA * xr[i]; acc[mt][nt][i] = v; s += v; ss += v * v; }
;             }
;             s2[mh] = s; ss2[mh] = ss;
;         }
; #pragma unroll
;         for (int mh = 0; mh < 2; ++mh) { s2[mh] += __shfl_xor(s2[mh], 16); ss2[mh] += __shfl_xor(ss2[mh], 16); }
; #pragma unroll
;         for (int mh = 0; mh < 2; ++mh) { s2[mh] += __shfl_xor(s2[mh], 32); ss2[mh] += __shfl_xor(ss2[mh], 32); }
;         if (quad == 0) {
; #pragma unroll
;             for (int mh = 0; mh < 2; ++mh) *(f32x2*)&red[((mh * 16 + l15) * 8 + wid) * 2] = (f32x2){s2[mh], ss2[mh]};
;         }
;         __syncthreads();
;         if (half == 0) issue_x(1);
; #pragma unroll
;         for (int mh = 0; mh < 2; ++mh) {
;             const int mt = half * 2 + mh, rl = mh * 16 + l15, row = mt * 16 + l15;
;             float s = 0.f, ss = 0.f;
; #pragma unroll
;             for (int w = 0; w < 4; ++w) { const f32x4 v = *(const f32x4*)&red[rl * 16 + 4 * w]; s += v[0] + v[2]; ss += v[1] + v[3]; }
;             const float mu = s * (1.f / 1024.f);
;             const float var = ss * (1.f / 1024.f) - mu * mu;
;             const float rs = rsqrtf(var + LN_EPS);
;             float* orow = xo + (r0 + row) * 1024 + wid * 128 + quad * 4;
;             bf16_t* brow = xbo + xb_off((int)r0 + row, wid * 128) + quad * 4;
;             const float* gp = GB + wid * 128 + quad * 4;
; #pragma unroll
;             for (int nt = 0; nt < 8; ++nt) {
	ds_read_b128 v[144:147], v200
	ds_read_b128 v[148:151], v201
	ds_read_b128 v[152:155], v202
	ds_read_b128 v[156:159], v203
	ds_read_b128 v[160:163], v200 offset:256
	ds_read_b128 v[164:167], v201 offset:256
	ds_read_b128 v[168:171], v202 offset:256
	ds_read_b128 v[172:175], v203 offset:256
	s_waitcnt lgkmcnt(7)
	v_fmac_f32_e32 v34, s58, v144
	v_fmac_f32_e32 v35, s58, v145
	v_fmac_f32_e32 v36, s58, v146
	v_fmac_f32_e32 v37, s58, v147
	v_mov_b32_e32 v196, v34
	v_mul_f32_e32 v197, v34, v34
	v_mov_b32_e32 v130, v35
	v_mul_f32_e32 v142, v35, v35
	v_add_f32_e32 v196, v196, v36
	v_fmac_f32_e32 v197, v36, v36
	v_add_f32_e32 v130, v130, v37
	v_fmac_f32_e32 v142, v37, v37
	s_waitcnt lgkmcnt(6)
	v_fmac_f32_e32 v30, s58, v148
	v_fmac_f32_e32 v31, s58, v149
	v_fmac_f32_e32 v32, s58, v150
	v_fmac_f32_e32 v33, s58, v151
	v_add_f32_e32 v196, v196, v30
	v_fmac_f32_e32 v197, v30, v30
	v_add_f32_e32 v130, v130, v31
	v_fmac_f32_e32 v142, v31, v31
	v_add_f32_e32 v196, v196, v32
	v_fmac_f32_e32 v197, v32, v32
	v_add_f32_e32 v130, v130, v33
	v_fmac_f32_e32 v142, v33, v33
	s_waitcnt lgkmcnt(5)
	v_fmac_f32_e32 v26, s58, v152
	v_fmac_f32_e32 v27, s58, v153
	v_fmac_f32_e32 v28, s58, v154
	v_fmac_f32_e32 v29, s58, v155
	v_add_f32_e32 v196, v196, v26
	v_fmac_f32_e32 v197, v26, v26
	v_add_f32_e32 v130, v130, v27
	v_fmac_f32_e32 v142, v27, v27
	v_add_f32_e32 v196, v196, v28
	v_fmac_f32_e32 v197, v28, v28
	v_add_f32_e32 v130, v130, v29
	v_fmac_f32_e32 v142, v29, v29
	s_waitcnt lgkmcnt(4)
	v_fmac_f32_e32 v22, s58, v156
	v_fmac_f32_e32 v23, s58, v157
	v_fmac_f32_e32 v24, s58, v158
	v_fmac_f32_e32 v25, s58, v159
	v_add_f32_e32 v196, v196, v22
	v_fmac_f32_e32 v197, v22, v22
	v_add_f32_e32 v130, v130, v23
	v_fmac_f32_e32 v142, v23, v23
	v_add_f32_e32 v196, v196, v24
	v_fmac_f32_e32 v197, v24, v24
	v_add_f32_e32 v130, v130, v25
	v_fmac_f32_e32 v142, v25, v25
	s_waitcnt lgkmcnt(3)
	v_fmac_f32_e32 v18, s58, v160
	v_fmac_f32_e32 v19, s58, v161
	v_fmac_f32_e32 v20, s58, v162
	v_fmac_f32_e32 v21, s58, v163
	v_add_f32_e32 v196, v196, v18
	v_fmac_f32_e32 v197, v18, v18
	v_add_f32_e32 v130, v130, v19
	v_fmac_f32_e32 v142, v19, v19
	v_add_f32_e32 v196, v196, v20
	v_fmac_f32_e32 v197, v20, v20
	v_add_f32_e32 v130, v130, v21
	v_fmac_f32_e32 v142, v21, v21
	s_waitcnt lgkmcnt(2)
	v_fmac_f32_e32 v14, s58, v164
	v_fmac_f32_e32 v15, s58, v165
	v_fmac_f32_e32 v16, s58, v166
	v_fmac_f32_e32 v17, s58, v167
	v_add_f32_e32 v196, v196, v14
	v_fmac_f32_e32 v197, v14, v14
	v_add_f32_e32 v130, v130, v15
	v_fmac_f32_e32 v142, v15, v15
	v_add_f32_e32 v196, v196, v16
	v_fmac_f32_e32 v197, v16, v16
	v_add_f32_e32 v130, v130, v17
	v_fmac_f32_e32 v142, v17, v17
	s_waitcnt lgkmcnt(1)
	v_fmac_f32_e32 v10, s58, v168
	v_fmac_f32_e32 v11, s58, v169
	v_fmac_f32_e32 v12, s58, v170
	v_fmac_f32_e32 v13, s58, v171
	v_add_f32_e32 v196, v196, v10
	v_fmac_f32_e32 v197, v10, v10
	v_add_f32_e32 v130, v130, v11
	v_fmac_f32_e32 v142, v11, v11
	v_add_f32_e32 v196, v196, v12
	v_fmac_f32_e32 v197, v12, v12
	v_add_f32_e32 v130, v130, v13
	v_fmac_f32_e32 v142, v13, v13
	s_waitcnt lgkmcnt(0)
	v_fmac_f32_e32 v6, s58, v172
	v_fmac_f32_e32 v7, s58, v173
	v_fmac_f32_e32 v8, s58, v174
	v_fmac_f32_e32 v9, s58, v175
	v_add_f32_e32 v196, v196, v6
	v_fmac_f32_e32 v197, v6, v6
	v_add_f32_e32 v130, v130, v7
	v_fmac_f32_e32 v142, v7, v7
	v_add_f32_e32 v196, v196, v8
	v_fmac_f32_e32 v197, v8, v8
	v_add_f32_e32 v130, v130, v9
	v_fmac_f32_e32 v142, v9, v9
	v_add_f32_e32 v196, v196, v130
	v_add_f32_e32 v197, v197, v142
	v_mov_b32_e32 v198, v196
	v_mov_b32_e32 v199, v197
	s_nop 1
	v_permlane16_swap_b32 v198, v196
	v_permlane16_swap_b32 v199, v197
	v_add_f32_e32 v196, v196, v198
	v_add_f32_e32 v197, v197, v199
	v_mov_b32_e32 v198, v196
	v_mov_b32_e32 v199, v197
	s_nop 1
	v_permlane32_swap_b32 v198, v196
	v_permlane32_swap_b32 v199, v197
	v_add_f32_e32 v196, v196, v198
	v_add_f32_e32 v197, v197, v199
	s_mov_b64 exec, 0xffff
	ds_write_b64 v134, v[196:197]
	s_mov_b64 exec, -1
	s_waitcnt lgkmcnt(0)
	s_barrier
	ds_read_b128 v[160:163], v135 offset:0
	ds_read_b128 v[164:167], v135 offset:16
	ds_read_b128 v[168:171], v135 offset:32
	ds_read_b128 v[172:175], v135 offset:48
	s_waitcnt lgkmcnt(0)
	v_add_f32_e32 v160, v160, v162
	v_add_f32_e32 v161, v161, v163
	v_add_f32_e32 v164, v164, v166
	v_add_f32_e32 v165, v165, v167
	v_add_f32_e32 v168, v168, v170
	v_add_f32_e32 v169, v169, v171
	v_add_f32_e32 v172, v172, v174
	v_add_f32_e32 v173, v173, v175
	v_add_f32_e32 v160, v160, v164
	v_add_f32_e32 v161, v161, v165
	v_add_f32_e32 v168, v168, v172
	v_add_f32_e32 v169, v169, v173
	v_add_f32_e32 v160, v160, v168
	v_add_f32_e32 v161, v161, v169
	v_mul_f32_e32 v192, 0x3a800000, v160
	v_mul_f32_e32 v193, 0x3a800000, v161
	v_fma_f32 v193, -v192, v192, v193
	v_add_f32_e32 v193, 0x3727c5ac, v193
	v_rsq_f32_e32 v193, v193
	s_nop 0
	s_add_u32 s94, s78, 0x800
	s_addc_u32 s95, s79, 0
	ds_read_b128 v[176:179], v136
	ds_read_b128 v[180:183], v136 offset:4096
	ds_read_b128 v[184:187], v136 offset:64
	ds_read_b128 v[188:191], v136 offset:4160
	s_waitcnt lgkmcnt(2)
	v_sub_f32_e32 v34, v34, v192
	v_mul_f32_e32 v34, v34, v193
	v_fma_f32 v34, v176, v34, v180
	v_sub_f32_e32 v35, v35, v192
	v_mul_f32_e32 v35, v35, v193
	v_fma_f32 v35, v177, v35, v181
	v_sub_f32_e32 v36, v36, v192
	v_mul_f32_e32 v36, v36, v193
	v_fma_f32 v36, v178, v36, v182
	v_sub_f32_e32 v37, v37, v192
	v_mul_f32_e32 v37, v37, v193
	v_fma_f32 v37, v179, v37, v183
	v_cvt_pk_bf16_f32 v144, v34, v35
	v_cvt_pk_bf16_f32 v145, v36, v37
	ds_read_b128 v[176:179], v136 offset:128
	ds_read_b128 v[180:183], v136 offset:4224
	s_waitcnt lgkmcnt(2)
; DI unsigned pk2(float lo, float hi) { const f32x2 v = {lo, hi}; const bf16x2_t b = __builtin_convertvector(v, bf16x2_t); return __builtin_bit_cast(unsigned, b); }
; DI size_t xb_off(int tok, int col) { return ((size_t)(((tok >> 7) * 32 + (col >> 5)) * 128 + (tok & 127))) * 32 + (col & 31); }
; DI void unit_O(const Params& p, char* lds, int l, int tile, int glu_tiles, int tile_b) {
;     ...
;             float* orow = xo + (r0 + row) * 1024 + wid * 128 + quad * 4;
;             bf16_t* brow = xbo + xb_off((int)r0 + row, wid * 128) + quad * 4;
;             const float* gp = GB + wid * 128 + quad * 4;
; #pragma unroll
;             for (int nt = 0; nt < 8; ++nt) {
;                 const f32x4 g = *(const f32x4*)(gp + nt * 16), bb = *(const f32x4*)(gp + 1024 + nt * 16);
;                 f32x4 o;
; #pragma unroll
;                 for (int i = 0; i < 4; ++i) o[i] = (acc[mt][nt][i] - mu) * rs * g[i] + bb[i];
;                 if (l == 0) *(u32x2*)(brow + (nt >> 1) * 4096 + (nt & 1) * 16) = (u32x2){pk2(o[0], o[1]), pk2(o[2], o[3])};
;                 else *(f32x4*)(orow + nt * 16) = o;
;             }
;         }
	v_sub_f32_e32 v30, v30, v192
	v_mul_f32_e32 v30, v30, v193
	v_fma_f32 v30, v184, v30, v188
	v_sub_f32_e32 v31, v31, v192
	v_mul_f32_e32 v31, v31, v193
	v_fma_f32 v31, v185, v31, v189
	v_sub_f32_e32 v32, v32, v192
	v_mul_f32_e32 v32, v32, v193
	v_fma_f32 v32, v186, v32, v190
	v_sub_f32_e32 v33, v33, v192
	v_mul_f32_e32 v33, v33, v193
	v_fma_f32 v33, v187, v33, v191
	v_cvt_pk_bf16_f32 v146, v30, v31
	v_cvt_pk_bf16_f32 v147, v32, v33
	s_nop 1
	v_permlane16_swap_b32 v144, v146
	v_permlane16_swap_b32 v145, v147
	global_store_dwordx4 v137, v[144:147], s[94:95]
	s_add_u32 s94, s94, 0x2000
	s_addc_u32 s95, s95, 0
	ds_read_b128 v[184:187], v136 offset:192
	ds_read_b128 v[188:191], v136 offset:4288
	s_waitcnt lgkmcnt(2)
	v_sub_f32_e32 v26, v26, v192
	v_mul_f32_e32 v26, v26, v193
	v_fma_f32 v26, v176, v26, v180
	v_sub_f32_e32 v27, v27, v192
	v_mul_f32_e32 v27, v27, v193
	v_fma_f32 v27, v177, v27, v181
	v_sub_f32_e32 v28, v28, v192
	v_mul_f32_e32 v28, v28, v193
	v_fma_f32 v28, v178, v28, v182
	v_sub_f32_e32 v29, v29, v192
	v_mul_f32_e32 v29, v29, v193
	v_fma_f32 v29, v179, v29, v183
	v_cvt_pk_bf16_f32 v152, v26, v27
	v_cvt_pk_bf16_f32 v153, v28, v29
	ds_read_b128 v[176:179], v136 offset:256
	ds_read_b128 v[180:183], v136 offset:4352
	s_waitcnt lgkmcnt(2)
	v_sub_f32_e32 v22, v22, v192
	v_mul_f32_e32 v22, v22, v193
	v_fma_f32 v22, v184, v22, v188
	v_sub_f32_e32 v23, v23, v192
	v_mul_f32_e32 v23, v23, v193
	v_fma_f32 v23, v185, v23, v189
	v_sub_f32_e32 v24, v24, v192
	v_mul_f32_e32 v24, v24, v193
	v_fma_f32 v24, v186, v24, v190
	v_sub_f32_e32 v25, v25, v192
	v_mul_f32_e32 v25, v25, v193
	v_fma_f32 v25, v187, v25, v191
	v_cvt_pk_bf16_f32 v154, v22, v23
	v_cvt_pk_bf16_f32 v155, v24, v25
	s_nop 1
	v_permlane16_swap_b32 v152, v154
	v_permlane16_swap_b32 v153, v155
	global_store_dwordx4 v137, v[152:155], s[94:95]
	s_add_u32 s94, s94, 0x2000
	s_addc_u32 s95, s95, 0
	ds_read_b128 v[184:187], v136 offset:320
	ds_read_b128 v[188:191], v136 offset:4416
	s_waitcnt lgkmcnt(2)
	v_sub_f32_e32 v18, v18, v192
	v_mul_f32_e32 v18, v18, v193
	v_fma_f32 v18, v176, v18, v180
	v_sub_f32_e32 v19, v19, v192
	v_mul_f32_e32 v19, v19, v193
	v_fma_f32 v19, v177, v19, v181
	v_sub_f32_e32 v20, v20, v192
	v_mul_f32_e32 v20, v20, v193
	v_fma_f32 v20, v178, v20, v182
	v_sub_f32_e32 v21, v21, v192
	v_mul_f32_e32 v21, v21, v193
	v_fma_f32 v21, v179, v21, v183
	v_cvt_pk_bf16_f32 v144, v18, v19
	v_cvt_pk_bf16_f32 v145, v20, v21
	ds_read_b128 v[176:179], v136 offset:384
	ds_read_b128 v[180:183], v136 offset:4480
	s_waitcnt lgkmcnt(2)
	v_sub_f32_e32 v14, v14, v192
	v_mul_f32_e32 v14, v14, v193
	v_fma_f32 v14, v184, v14, v188
	v_sub_f32_e32 v15, v15, v192
	v_mul_f32_e32 v15, v15, v193
	v_fma_f32 v15, v185, v15, v189
	v_sub_f32_e32 v16, v16, v192
	v_mul_f32_e32 v16, v16, v193
	v_fma_f32 v16, v186, v16, v190
	v_sub_f32_e32 v17, v17, v192
	v_mul_f32_e32 v17, v17, v193
	v_fma_f32 v17, v187, v17, v191
	v_cvt_pk_bf16_f32 v146, v14, v15
	v_cvt_pk_bf16_f32 v147, v16, v17
	s_nop 1
	v_permlane16_swap_b32 v144, v146
	v_permlane16_swap_b32 v145, v147
	global_store_dwordx4 v137, v[144:147], s[94:95]
	s_add_u32 s94, s94, 0x2000
	s_addc_u32 s95, s95, 0
	ds_read_b128 v[184:187], v136 offset:448
	ds_read_b128 v[188:191], v136 offset:4544
	s_waitcnt lgkmcnt(2)
	v_sub_f32_e32 v10, v10, v192
	v_mul_f32_e32 v10, v10, v193
	v_fma_f32 v10, v176, v10, v180
	v_sub_f32_e32 v11, v11, v192
	v_mul_f32_e32 v11, v11, v193
	v_fma_f32 v11, v177, v11, v181
	v_sub_f32_e32 v12, v12, v192
	v_mul_f32_e32 v12, v12, v193
	v_fma_f32 v12, v178, v12, v182
	v_sub_f32_e32 v13, v13, v192
	v_mul_f32_e32 v13, v13, v193
	v_fma_f32 v13, v179, v13, v183
	v_cvt_pk_bf16_f32 v152, v10, v11
	v_cvt_pk_bf16_f32 v153, v12, v13
	s_waitcnt lgkmcnt(0)
	v_sub_f32_e32 v6, v6, v192
	v_mul_f32_e32 v6, v6, v193
	v_fma_f32 v6, v184, v6, v188
	v_sub_f32_e32 v7, v7, v192
	v_mul_f32_e32 v7, v7, v193
	v_fma_f32 v7, v185, v7, v189
	v_sub_f32_e32 v8, v8, v192
	v_mul_f32_e32 v8, v8, v193
	v_fma_f32 v8, v186, v8, v190
	v_sub_f32_e32 v9, v9, v192
	v_mul_f32_e32 v9, v9, v193
	v_fma_f32 v9, v187, v9, v191
	v_cvt_pk_bf16_f32 v154, v6, v7
	v_cvt_pk_bf16_f32 v155, v8, v9
	s_nop 1
	v_permlane16_swap_b32 v152, v154
	v_permlane16_swap_b32 v153, v155
	global_store_dwordx4 v137, v[152:155], s[94:95]
	s_waitcnt vmcnt(8) lgkmcnt(0)
	s_barrier
; DI float bf2f(unsigned b) { return __uint_as_float(b << 16); }
; DI void unit_O(const Params& p, char* lds, int l, int tile, int glu_tiles, int tile_b) {
;     ...
;         float s2[2], ss2[2];
; #pragma unroll
;         for (int mh = 0; mh < 2; ++mh) {
;             const int mt = half * 2 + mh, rl = mh * 16 + l15;
;             float s = 0.f, ss = 0.f;
; #pragma unroll
;             for (int nt = 0; nt < 8; ++nt) {
;                 f32x4 xr;
;                 if (l == 0) {
;                     const int chunk = wid * 32 + nt * 4 + quad;
;                     xr = *(const f32x4*)(XR + rl * 4096 + ((chunk ^ l15) << 4));
;                 } else {
;                     const u32x2 hb = *(const u32x2*)(XR + ((wid * 4 + (nt >> 1)) * 32 + rl) * 64 + (nt & 1) * 32 + quad * 8);
;                     xr = (f32x4){bf2f(hb[0] & 0xffffu), bf2f(hb[0] >> 16), bf2f(hb[1] & 0xffffu), bf2f(hb[1] >> 16)};
;                 }
; #pragma unroll
;                 for (int i = 0; i < 4; ++i) { const float v = acc[mt][nt][i] + DN_ALPHA * xr[i]; acc[mt][nt][i] = v; s += v; ss += v * v; }
;             }
;             s2[mh] = s; ss2[mh] = ss;
;         }
; #pragma unroll
;         for (int mh = 0; mh < 2; ++mh) { s2[mh] += __shfl_xor(s2[mh], 16); ss2[mh] += __shfl_xor(ss2[mh], 16); }
; #pragma unroll
;         for (int mh = 0; mh < 2; ++mh) { s2[mh] += __shfl_xor(s2[mh], 32); ss2[mh] += __shfl_xor(ss2[mh], 32); }
;         if (quad == 0) {
; #pragma unroll
;             for (int mh = 0; mh < 2; ++mh) *(f32x2*)&red[((mh * 16 + l15) * 8 + wid) * 2] = (f32x2){s2[mh], ss2[mh]};
;         }
;         __syncthreads();
	ds_read_b128 v[144:147], v204
	ds_read_b128 v[148:151], v205
	ds_read_b128 v[152:155], v206
	ds_read_b128 v[156:159], v207
	ds_read_b128 v[160:163], v204 offset:256
	ds_read_b128 v[164:167], v205 offset:256
	ds_read_b128 v[168:171], v206 offset:256
	ds_read_b128 v[172:175], v207 offset:256
	s_waitcnt lgkmcnt(7)
	v_fmac_f32_e32 v62, s58, v144
	v_fmac_f32_e32 v63, s58, v145
	v_fmac_f32_e32 v64, s58, v146
	v_fmac_f32_e32 v65, s58, v147
	v_mov_b32_e32 v196, v62
	v_mul_f32_e32 v197, v62, v62
	v_mov_b32_e32 v130, v63
	v_mul_f32_e32 v142, v63, v63
	v_add_f32_e32 v196, v196, v64
	v_fmac_f32_e32 v197, v64, v64
	v_add_f32_e32 v130, v130, v65
	v_fmac_f32_e32 v142, v65, v65
	s_waitcnt lgkmcnt(6)
	v_fmac_f32_e32 v58, s58, v148
	v_fmac_f32_e32 v59, s58, v149
	v_fmac_f32_e32 v60, s58, v150
	v_fmac_f32_e32 v61, s58, v151
	v_add_f32_e32 v196, v196, v58
	v_fmac_f32_e32 v197, v58, v58
	v_add_f32_e32 v130, v130, v59
	v_fmac_f32_e32 v142, v59, v59
	v_add_f32_e32 v196, v196, v60
	v_fmac_f32_e32 v197, v60, v60
	v_add_f32_e32 v130, v130, v61
	v_fmac_f32_e32 v142, v61, v61
	s_waitcnt lgkmcnt(5)
	v_fmac_f32_e32 v54, s58, v152
	v_fmac_f32_e32 v55, s58, v153
	v_fmac_f32_e32 v56, s58, v154
	v_fmac_f32_e32 v57, s58, v155
	v_add_f32_e32 v196, v196, v54
	v_fmac_f32_e32 v197, v54, v54
	v_add_f32_e32 v130, v130, v55
	v_fmac_f32_e32 v142, v55, v55
	v_add_f32_e32 v196, v196, v56
	v_fmac_f32_e32 v197, v56, v56
	v_add_f32_e32 v130, v130, v57
	v_fmac_f32_e32 v142, v57, v57
	s_waitcnt lgkmcnt(4)
	v_fmac_f32_e32 v50, s58, v156
	v_fmac_f32_e32 v51, s58, v157
	v_fmac_f32_e32 v52, s58, v158
	v_fmac_f32_e32 v53, s58, v159
	v_add_f32_e32 v196, v196, v50
	v_fmac_f32_e32 v197, v50, v50
	v_add_f32_e32 v130, v130, v51
	v_fmac_f32_e32 v142, v51, v51
	v_add_f32_e32 v196, v196, v52
	v_fmac_f32_e32 v197, v52, v52
	v_add_f32_e32 v130, v130, v53
	v_fmac_f32_e32 v142, v53, v53
	s_waitcnt lgkmcnt(3)
	v_fmac_f32_e32 v46, s58, v160
	v_fmac_f32_e32 v47, s58, v161
	v_fmac_f32_e32 v48, s58, v162
	v_fmac_f32_e32 v49, s58, v163
	v_add_f32_e32 v196, v196, v46
	v_fmac_f32_e32 v197, v46, v46
	v_add_f32_e32 v130, v130, v47
	v_fmac_f32_e32 v142, v47, v47
	v_add_f32_e32 v196, v196, v48
	v_fmac_f32_e32 v197, v48, v48
	v_add_f32_e32 v130, v130, v49
	v_fmac_f32_e32 v142, v49, v49
	s_waitcnt lgkmcnt(2)
	v_fmac_f32_e32 v42, s58, v164
	v_fmac_f32_e32 v43, s58, v165
	v_fmac_f32_e32 v44, s58, v166
	v_fmac_f32_e32 v45, s58, v167
	v_add_f32_e32 v196, v196, v42
	v_fmac_f32_e32 v197, v42, v42
	v_add_f32_e32 v130, v130, v43
	v_fmac_f32_e32 v142, v43, v43
	v_add_f32_e32 v196, v196, v44
	v_fmac_f32_e32 v197, v44, v44
	v_add_f32_e32 v130, v130, v45
	v_fmac_f32_e32 v142, v45, v45
	s_waitcnt lgkmcnt(1)
	v_fmac_f32_e32 v38, s58, v168
	v_fmac_f32_e32 v39, s58, v169
	v_fmac_f32_e32 v40, s58, v170
	v_fmac_f32_e32 v41, s58, v171
	v_add_f32_e32 v196, v196, v38
	v_fmac_f32_e32 v197, v38, v38
	v_add_f32_e32 v130, v130, v39
	v_fmac_f32_e32 v142, v39, v39
	v_add_f32_e32 v196, v196, v40
	v_fmac_f32_e32 v197, v40, v40
	v_add_f32_e32 v130, v130, v41
	v_fmac_f32_e32 v142, v41, v41
	s_waitcnt lgkmcnt(0)
	v_fmac_f32_e32 v2, s58, v172
	v_fmac_f32_e32 v3, s58, v173
	v_fmac_f32_e32 v4, s58, v174
	v_fmac_f32_e32 v5, s58, v175
	v_add_f32_e32 v196, v196, v2
	v_fmac_f32_e32 v197, v2, v2
	v_add_f32_e32 v130, v130, v3
	v_fmac_f32_e32 v142, v3, v3
	v_add_f32_e32 v196, v196, v4
	v_fmac_f32_e32 v197, v4, v4
	v_add_f32_e32 v130, v130, v5
	v_fmac_f32_e32 v142, v5, v5
	v_add_f32_e32 v196, v196, v130
	v_add_f32_e32 v197, v197, v142
	v_mov_b32_e32 v198, v196
	v_mov_b32_e32 v199, v197
	s_nop 1
	v_permlane16_swap_b32 v198, v196
	v_permlane16_swap_b32 v199, v197
	v_add_f32_e32 v196, v196, v198
	v_add_f32_e32 v197, v197, v199
	v_mov_b32_e32 v198, v196
	v_mov_b32_e32 v199, v197
	s_nop 1
	v_permlane32_swap_b32 v198, v196
	v_permlane32_swap_b32 v199, v197
	v_add_f32_e32 v196, v196, v198
	v_add_f32_e32 v197, v197, v199
	s_mov_b64 exec, 0xffff
	ds_write_b64 v134, v[196:197]
	s_mov_b64 exec, -1
	s_waitcnt lgkmcnt(0)
	s_barrier
; DI unsigned pk2(float lo, float hi) { const f32x2 v = {lo, hi}; const bf16x2_t b = __builtin_convertvector(v, bf16x2_t); return __builtin_bit_cast(unsigned, b); }
; DI size_t xb_off(int tok, int col) { return ((size_t)(((tok >> 7) * 32 + (col >> 5)) * 128 + (tok & 127))) * 32 + (col & 31); }
; DI void unit_O(const Params& p, char* lds, int l, int tile, int glu_tiles, int tile_b) {
;     ...
;         for (int mh = 0; mh < 2; ++mh) {
;             const int mt = half * 2 + mh, rl = mh * 16 + l15, row = mt * 16 + l15;
;             float s = 0.f, ss = 0.f;
; #pragma unroll
;             for (int w = 0; w < 4; ++w) { const f32x4 v = *(const f32x4*)&red[rl * 16 + 4 * w]; s += v[0] + v[2]; ss += v[1] + v[3]; }
;             const float mu = s * (1.f / 1024.f);
;             const float var = ss * (1.f / 1024.f) - mu * mu;
;             const float rs = rsqrtf(var + LN_EPS);
;             float* orow = xo + (r0 + row) * 1024 + wid * 128 + quad * 4;
;             bf16_t* brow = xbo + xb_off((int)r0 + row, wid * 128) + quad * 4;
;             const float* gp = GB + wid * 128 + quad * 4;
; #pragma unroll
;             for (int nt = 0; nt < 8; ++nt) {
;                 const f32x4 g = *(const f32x4*)(gp + nt * 16), bb = *(const f32x4*)(gp + 1024 + nt * 16);
;                 f32x4 o;
; #pragma unroll
;                 for (int i = 0; i < 4; ++i) o[i] = (acc[mt][nt][i] - mu) * rs * g[i] + bb[i];
;                 if (l == 0) *(u32x2*)(brow + (nt >> 1) * 4096 + (nt & 1) * 16) = (u32x2){pk2(o[0], o[1]), pk2(o[2], o[3])};
;                 else *(f32x4*)(orow + nt * 16) = o;
;             }
;         }
	ds_read_b128 v[160:163], v135 offset:0
	ds_read_b128 v[164:167], v135 offset:16
	ds_read_b128 v[168:171], v135 offset:32
	ds_read_b128 v[172:175], v135 offset:48
	s_waitcnt lgkmcnt(0)
	v_add_f32_e32 v160, v160, v162
	v_add_f32_e32 v161, v161, v163
	v_add_f32_e32 v164, v164, v166
	v_add_f32_e32 v165, v165, v167
	v_add_f32_e32 v168, v168, v170
	v_add_f32_e32 v169, v169, v171
	v_add_f32_e32 v172, v172, v174
	v_add_f32_e32 v173, v173, v175
	v_add_f32_e32 v160, v160, v164
	v_add_f32_e32 v161, v161, v165
	v_add_f32_e32 v168, v168, v172
	v_add_f32_e32 v169, v169, v173
	v_add_f32_e32 v160, v160, v168
	v_add_f32_e32 v161, v161, v169
	v_mul_f32_e32 v192, 0x3a800000, v160
	v_mul_f32_e32 v193, 0x3a800000, v161
	v_fma_f32 v193, -v192, v192, v193
	v_add_f32_e32 v193, 0x3727c5ac, v193
	v_rsq_f32_e32 v193, v193
	s_nop 0
	s_add_u32 s94, s78, 0xc00
	s_addc_u32 s95, s79, 0
	ds_read_b128 v[176:179], v136
	ds_read_b128 v[180:183], v136 offset:4096
	ds_read_b128 v[184:187], v136 offset:64
	ds_read_b128 v[188:191], v136 offset:4160
	s_waitcnt lgkmcnt(2)
	v_sub_f32_e32 v62, v62, v192
	v_mul_f32_e32 v62, v62, v193
	v_fma_f32 v62, v176, v62, v180
	v_sub_f32_e32 v63, v63, v192
	v_mul_f32_e32 v63, v63, v193
	v_fma_f32 v63, v177, v63, v181
	v_sub_f32_e32 v64, v64, v192
	v_mul_f32_e32 v64, v64, v193
	v_fma_f32 v64, v178, v64, v182
	v_sub_f32_e32 v65, v65, v192
	v_mul_f32_e32 v65, v65, v193
	v_fma_f32 v65, v179, v65, v183
	v_cvt_pk_bf16_f32 v144, v62, v63
	v_cvt_pk_bf16_f32 v145, v64, v65
	ds_read_b128 v[176:179], v136 offset:128
	ds_read_b128 v[180:183], v136 offset:4224
	s_waitcnt lgkmcnt(2)
	v_sub_f32_e32 v58, v58, v192
	v_mul_f32_e32 v58, v58, v193
	v_fma_f32 v58, v184, v58, v188
	v_sub_f32_e32 v59, v59, v192
	v_mul_f32_e32 v59, v59, v193
	v_fma_f32 v59, v185, v59, v189
	v_sub_f32_e32 v60, v60, v192
	v_mul_f32_e32 v60, v60, v193
	v_fma_f32 v60, v186, v60, v190
	v_sub_f32_e32 v61, v61, v192
	v_mul_f32_e32 v61, v61, v193
	v_fma_f32 v61, v187, v61, v191
	v_cvt_pk_bf16_f32 v146, v58, v59
	v_cvt_pk_bf16_f32 v147, v60, v61
	s_nop 1
	v_permlane16_swap_b32 v144, v146
	v_permlane16_swap_b32 v145, v147
	global_store_dwordx4 v137, v[144:147], s[94:95]
	s_add_u32 s94, s94, 0x2000
	s_addc_u32 s95, s95, 0
	ds_read_b128 v[184:187], v136 offset:192
	ds_read_b128 v[188:191], v136 offset:4288
	s_waitcnt lgkmcnt(2)
	v_sub_f32_e32 v54, v54, v192
	v_mul_f32_e32 v54, v54, v193
	v_fma_f32 v54, v176, v54, v180
	v_sub_f32_e32 v55, v55, v192
	v_mul_f32_e32 v55, v55, v193
	v_fma_f32 v55, v177, v55, v181
	v_sub_f32_e32 v56, v56, v192
	v_mul_f32_e32 v56, v56, v193
	v_fma_f32 v56, v178, v56, v182
	v_sub_f32_e32 v57, v57, v192
	v_mul_f32_e32 v57, v57, v193
	v_fma_f32 v57, v179, v57, v183
	v_cvt_pk_bf16_f32 v152, v54, v55
	v_cvt_pk_bf16_f32 v153, v56, v57
	ds_read_b128 v[176:179], v136 offset:256
	ds_read_b128 v[180:183], v136 offset:4352
	s_waitcnt lgkmcnt(2)
	v_sub_f32_e32 v50, v50, v192
	v_mul_f32_e32 v50, v50, v193
	v_fma_f32 v50, v184, v50, v188
	v_sub_f32_e32 v51, v51, v192
	v_mul_f32_e32 v51, v51, v193
	v_fma_f32 v51, v185, v51, v189
	v_sub_f32_e32 v52, v52, v192
	v_mul_f32_e32 v52, v52, v193
	v_fma_f32 v52, v186, v52, v190
	v_sub_f32_e32 v53, v53, v192
	v_mul_f32_e32 v53, v53, v193
	v_fma_f32 v53, v187, v53, v191
	v_cvt_pk_bf16_f32 v154, v50, v51
	v_cvt_pk_bf16_f32 v155, v52, v53
	s_nop 1
	v_permlane16_swap_b32 v152, v154
	v_permlane16_swap_b32 v153, v155
	global_store_dwordx4 v137, v[152:155], s[94:95]
	s_add_u32 s94, s94, 0x2000
	s_addc_u32 s95, s95, 0
	ds_read_b128 v[184:187], v136 offset:320
	ds_read_b128 v[188:191], v136 offset:4416
	s_waitcnt lgkmcnt(2)
	v_sub_f32_e32 v46, v46, v192
	v_mul_f32_e32 v46, v46, v193
	v_fma_f32 v46, v176, v46, v180
	v_sub_f32_e32 v47, v47, v192
	v_mul_f32_e32 v47, v47, v193
	v_fma_f32 v47, v177, v47, v181
	v_sub_f32_e32 v48, v48, v192
	v_mul_f32_e32 v48, v48, v193
	v_fma_f32 v48, v178, v48, v182
	v_sub_f32_e32 v49, v49, v192
	v_mul_f32_e32 v49, v49, v193
	v_fma_f32 v49, v179, v49, v183
	v_cvt_pk_bf16_f32 v144, v46, v47
	v_cvt_pk_bf16_f32 v145, v48, v49
	ds_read_b128 v[176:179], v136 offset:384
	ds_read_b128 v[180:183], v136 offset:4480
	s_waitcnt lgkmcnt(2)
	v_sub_f32_e32 v42, v42, v192
	v_mul_f32_e32 v42, v42, v193
	v_fma_f32 v42, v184, v42, v188
	v_sub_f32_e32 v43, v43, v192
	v_mul_f32_e32 v43, v43, v193
	v_fma_f32 v43, v185, v43, v189
	v_sub_f32_e32 v44, v44, v192
	v_mul_f32_e32 v44, v44, v193
	v_fma_f32 v44, v186, v44, v190
	v_sub_f32_e32 v45, v45, v192
	v_mul_f32_e32 v45, v45, v193
	v_fma_f32 v45, v187, v45, v191
	v_cvt_pk_bf16_f32 v146, v42, v43
	v_cvt_pk_bf16_f32 v147, v44, v45
	s_nop 1
	v_permlane16_swap_b32 v144, v146
	v_permlane16_swap_b32 v145, v147
	global_store_dwordx4 v137, v[144:147], s[94:95]
	s_add_u32 s94, s94, 0x2000
	s_addc_u32 s95, s95, 0
	ds_read_b128 v[184:187], v136 offset:448
	ds_read_b128 v[188:191], v136 offset:4544
	s_waitcnt lgkmcnt(2)
	v_sub_f32_e32 v38, v38, v192
	v_mul_f32_e32 v38, v38, v193
	v_fma_f32 v38, v176, v38, v180
	v_sub_f32_e32 v39, v39, v192
	v_mul_f32_e32 v39, v39, v193
	v_fma_f32 v39, v177, v39, v181
	v_sub_f32_e32 v40, v40, v192
	v_mul_f32_e32 v40, v40, v193
	v_fma_f32 v40, v178, v40, v182
	v_sub_f32_e32 v41, v41, v192
	v_mul_f32_e32 v41, v41, v193
	v_fma_f32 v41, v179, v41, v183
	v_cvt_pk_bf16_f32 v152, v38, v39
	v_cvt_pk_bf16_f32 v153, v40, v41
	s_waitcnt lgkmcnt(0)
	v_sub_f32_e32 v2, v2, v192
	v_mul_f32_e32 v2, v2, v193
	v_fma_f32 v2, v184, v2, v188
	v_sub_f32_e32 v3, v3, v192
	v_mul_f32_e32 v3, v3, v193
	v_fma_f32 v3, v185, v3, v189
	v_sub_f32_e32 v4, v4, v192
	v_mul_f32_e32 v4, v4, v193
	v_fma_f32 v4, v186, v4, v190
	v_sub_f32_e32 v5, v5, v192
	v_mul_f32_e32 v5, v5, v193
	v_fma_f32 v5, v187, v5, v191
	v_cvt_pk_bf16_f32 v154, v2, v3
	v_cvt_pk_bf16_f32 v155, v4, v5
	s_nop 1
	v_permlane16_swap_b32 v152, v154
	v_permlane16_swap_b32 v153, v155
	global_store_dwordx4 v137, v[152:155], s[94:95]
	s_branch .Le1_done

; template <int N> DI void wait_vm() { asm volatile("s_waitcnt vmcnt(%0)" ::"n"(N) : "memory"); }
; DI void raw_barrier() { asm volatile("" ::: "memory"); __builtin_amdgcn_s_barrier(); asm volatile("" ::: "memory"); }
;     ...
;     __syncthreads();
; #pragma unroll
;     for (int d = 0; d < D; ++d) issue(d, d);
;     int cb = 0, ib = D;
;     for (int kt = 0; kt < KT; ++kt) {
;         if (D > 1 && kt + D - 1 < KT) wait_vm<(D - 1) * NIT>(); else wait_vm<0>();
;         raw_barrier();
;         compute(cb, kt + D < KT, kt + D, ib);
;         cb = (cb + 1 == NST) ? 0 : cb + 1;
;         ib = (ib + 1 == NST) ? 0 : ib + 1;
;     }
.Lpo2_c_entry:
	v_subrev_u32_e32 v246, 0x100, v212
	v_readfirstlane_b32 s96, v130
	v_readfirstlane_b32 s97, v131
	v_readfirstlane_b32 s94, v0
	s_nop 3
	s_sub_u32 s96, s96, s94
	s_subb_u32 s97, s97, 0
	s_add_i32 s94, s33, 2
	v_lshrrev_b32_e32 v247, 5, v246
	v_add_u32_e32 v247, s94, v247
	v_and_b32_e32 v247, 31, v247
	v_and_b32_e32 v199, 31, v246
	v_lshlrev_b32_e32 v199, 7, v199
	v_lshl_or_b32 v247, v247, 12, v199
	s_nop 1
	global_load_dword v247, v247, s[96:97]
	v_readlane_b32 s91, v244, 36
	v_readfirstlane_b32 s95, v246
	s_nop 3
	s_lshr_b32 s91, s91, 3
	s_lshr_b32 s95, s95, 6
	s_mov_b32 s29, 2
	s_waitcnt vmcnt(1)
	s_barrier
	v_add_u32_e32 v197, v140, v141
	v_add_u32_e32 v196, v140, v139
	ds_read_b128 v[146:149], v196
	ds_read_b128 v[154:157], v196 offset:1024
	ds_read_b128 v[182:185], v196 offset:2048
	ds_read_b128 v[142:145], v197 offset:4096
	ds_read_b128 v[150:153], v197 offset:5120
	ds_read_b128 v[158:161], v197 offset:6144
	ds_read_b128 v[162:165], v197 offset:7168
	ds_read_b128 v[166:169], v197 offset:8192
	ds_read_b128 v[170:173], v197 offset:9216
	ds_read_b128 v[174:177], v197 offset:10240
	ds_read_b128 v[178:181], v197 offset:11264
	ds_read_b128 v[186:189], v196 offset:3072

; template <int N> DI void wait_vm() { asm volatile("s_waitcnt vmcnt(%0)" ::"n"(N) : "memory"); }
; DI void raw_barrier() { asm volatile("" ::: "memory"); __builtin_amdgcn_s_barrier(); asm volatile("" ::: "memory"); }
;     ...
;     for (int kt = 0; kt < KT; ++kt) {
;         if (D > 1 && kt + D - 1 < KT) wait_vm<(D - 1) * NIT>(); else wait_vm<0>();
;         raw_barrier();
;         compute(cb, kt + D < KT, kt + D, ib);
;         cb = (cb + 1 == NST) ? 0 : cb + 1;
;         ib = (ib + 1 == NST) ? 0 : ib + 1;
;     }
.Lpo2_ypf_skip:
	s_and_b32 s94, s29, 3
	s_cmp_lg_u32 s94, 2
	s_cbranch_scc1 .Lpo2_wpf_skip
	s_cmp_lg_u32 s95, 0
	s_cbranch_scc1 .Lpo2_wpf_skip
	s_lshr_b32 s94, s91, 3
	s_add_i32 s94, s94, s29
	s_add_i32 s94, s94, s33
	s_add_i32 s94, s94, 4
	s_and_b32 s94, s94, 31
	s_lshl_b32 s94, s94, 16
	s_and_b32 s92, s91, 7
	s_lshl_b32 s92, s92, 13
	s_add_u32 s94, s94, s92
	s_add_u32 s92, s18, s94
	s_addc_u32 s93, s19, 0
	v_lshlrev_b32_e32 v199, 7, v246
	global_load_dword v247, v199, s[92:93]
